# basket v1: removed per-segment s_setprio in all six GEMM main loops; sc1 write-through on 16B epilogue stores of P4/P10/P13; P13 full-tile residual epilogue with all loads hoisted
# baseline (speedup 1.0000x reference)
; #define PG8_STAGE(bufoff, gbase, voff) do { _Pragma("unroll") for (int _i = 0; _i < 2; ++_i) \
;         __builtin_amdgcn_global_load_lds((const unsigned*)((const char*)(gbase) + (voff)[_i]), (PG8_LAS unsigned*)(lds + (bufoff) + ldsw + _i * 8192), 16, 0, 0); } while (0)
; #define PG8_LDA(dst, b, h) do { _Pragma("unroll") for (int m = 0; m < 4; ++m) _Pragma("unroll") for (int k = 0; k < 2; ++k) dst[m][k] = *(const PG8_LAS bf16x8*)(lds + PG8_SA(b, h) + aoff + m * 2048 + k * 1024); } while (0)
; #define PG8_LDB(dst, b, h) do { _Pragma("unroll") for (int n = 0; n < 2; ++n) _Pragma("unroll") for (int k = 0; k < 2; ++k) dst[n][k] = *(const PG8_LAS bf16x8*)(lds + PG8_SB(b, h) + boff + n * 2048 + k * 1024); } while (0)
; #define PG8_MMA(ai, bj, At, Bt) do { __builtin_amdgcn_s_setprio(1); _Pragma("unroll") for (int m = 0; m < 4; ++m) _Pragma("unroll") for (int n = 0; n < 2; ++n) _Pragma("unroll") for (int k = 0; k < 2; ++k) \
;         acc[ai][bj][m][n] = __builtin_amdgcn_mfma_f32_16x16x32_bf16(Bt[n][k], At[m][k], acc[ai][bj][m][n], 0, 0, 0); __builtin_amdgcn_s_setprio(0); } while (0)
; #define PG8_WAIT_V(n) asm volatile("s_waitcnt vmcnt(" #n ")" ::: "memory")
; #define PG8_WAIT_L(n) asm volatile("s_waitcnt lgkmcnt(" #n ")" ::: "memory")
; #define PG8_BAR __builtin_amdgcn_s_barrier()
; template <class Epi, class Sched, bool ALIGN_EPI = false>
; __device__ __forceinline__ void gemm_phase8(PG8_LAS unsigned char* lds, const Gemm g, const Sched& S, const Epi& E) {
;     ...
;             const bool last = (t == nt - 2);
;             const char* a1 = cA + (size_t)(t + 1) * kstep;
;             const char* a2 = last ? nA : cA + (size_t)(t + 2) * kstep; const char* b2 = last ? nB : cB + (size_t)(t + 2) * kstep;
;             const char* a3 = a2 + kstep; const char* b3 = b2 + kstep;
;             if (last && has_next) S.a_ready(nxt);
;             PG8_LDB(B0, 0, 0); PG8_LDB(B1, 0, 1); PG8_SCHED; PG8_LDA(At, 0, 0); PG8_STAGE(PG8_SA(1, 1), a1 + hstepA, voffA);
;             PG8_WAIT_V(8); PG8_WAIT_L(0); PG8_BAR; PG8_MMA(0, 0, At, B0); PG8_MMA(0, 1, At, B1); PG8_BAR; PG8_SCHED;
;             PG8_LDA(At, 0, 1); PG8_STAGE(PG8_SB(0, 0), b2, voffB); PG8_STAGE(PG8_SB(0, 1), b2 + hstepB, voffB); PG8_STAGE(PG8_SA(0, 0), a2, voffA);
;             PG8_WAIT_V(8); PG8_WAIT_L(0); PG8_BAR; PG8_MMA(1, 0, At, B0); PG8_MMA(1, 1, At, B1); PG8_BAR; PG8_SCHED;
.LBB0_325:
	ds_read_b128 v[18:21], v191
	ds_read_b128 v[26:29], v191 offset:2048
	ds_read_b128 v[22:25], v192
	ds_read_b128 v[30:33], v192 offset:2048
	ds_read_b128 v[2:5], v193
	ds_read_b128 v[10:13], v193 offset:2048
	ds_read_b128 v[6:9], v194
	ds_read_b128 v[14:17], v194 offset:2048
	s_add_u32 s24, s22, 0xfffc0080
	s_addc_u32 s25, s23, -1
	s_cmp_eq_u32 s65, 12
	s_cselect_b32 s27, s15, s25
	s_cselect_b32 s26, s61, s24
	s_cselect_b32 s25, s13, s64
	s_cselect_b32 s24, s62, s63
	v_lshl_add_u64 v[222:223], s[22:23], 0, v[170:171]
	s_add_i32 m0, s21, 0xc000
	ds_read_b128 v[178:181], v195
	ds_read_b128 v[198:201], v195 offset:2048
	ds_read_b128 v[182:185], v196
	ds_read_b128 v[202:205], v196 offset:2048
	ds_read_b128 v[206:209], v195 offset:4096
	ds_read_b128 v[214:217], v195 offset:6144
	ds_read_b128 v[210:213], v196 offset:4096
	ds_read_b128 v[218:221], v196 offset:6144
	global_load_lds_dwordx4 v[222:223], off
	v_lshl_add_u64 v[222:223], s[22:23], 0, v[172:173]
	s_add_i32 m0, s21, 0xe000
	s_nop 0
	global_load_lds_dwordx4 v[222:223], off
	s_waitcnt vmcnt(8)
	s_waitcnt lgkmcnt(0)
	s_barrier
	s_waitcnt lgkmcnt(0)
	v_mfma_scale_f32_16x16x128_f8f6f4 v[158:161], v[18:25], v[178:185], v[158:161], v1, v186 op_sel_hi:[0,0,0]
	v_mfma_scale_f32_16x16x128_f8f6f4 v[150:153], v[26:33], v[178:185], v[150:153], v1, v186 op_sel_hi:[0,0,0]
	v_mfma_scale_f32_16x16x128_f8f6f4 v[142:145], v[18:25], v[198:205], v[142:145], v1, v186 op_sel_hi:[0,0,0]
	v_mfma_scale_f32_16x16x128_f8f6f4 v[134:137], v[26:33], v[198:205], v[134:137], v1, v186 op_sel_hi:[0,0,0]
	v_mfma_scale_f32_16x16x128_f8f6f4 v[126:129], v[18:25], v[206:213], v[126:129], v1, v186 op_sel_hi:[0,0,0]
	v_mfma_scale_f32_16x16x128_f8f6f4 v[118:121], v[26:33], v[206:213], v[118:121], v1, v186 op_sel_hi:[0,0,0]
	v_mfma_scale_f32_16x16x128_f8f6f4 v[110:113], v[18:25], v[214:221], v[110:113], v1, v186 op_sel_hi:[0,0,0]
	v_mfma_scale_f32_16x16x128_f8f6f4 v[102:105], v[26:33], v[214:221], v[102:105], v1, v186 op_sel_hi:[0,0,0]
	v_mfma_scale_f32_16x16x128_f8f6f4 v[154:157], v[2:9], v[178:185], v[154:157], v1, v186 op_sel_hi:[0,0,0]
	v_mfma_scale_f32_16x16x128_f8f6f4 v[146:149], v[10:17], v[178:185], v[146:149], v1, v186 op_sel_hi:[0,0,0]
	v_mfma_scale_f32_16x16x128_f8f6f4 v[138:141], v[2:9], v[198:205], v[138:141], v1, v186 op_sel_hi:[0,0,0]
	v_mfma_scale_f32_16x16x128_f8f6f4 v[130:133], v[10:17], v[198:205], v[130:133], v1, v186 op_sel_hi:[0,0,0]
	v_mfma_scale_f32_16x16x128_f8f6f4 v[122:125], v[2:9], v[206:213], v[122:125], v1, v186 op_sel_hi:[0,0,0]
	v_mfma_scale_f32_16x16x128_f8f6f4 v[114:117], v[10:17], v[206:213], v[114:117], v1, v186 op_sel_hi:[0,0,0]
	v_mfma_scale_f32_16x16x128_f8f6f4 v[106:109], v[2:9], v[214:221], v[106:109], v1, v186 op_sel_hi:[0,0,0]
	v_mfma_scale_f32_16x16x128_f8f6f4 v[98:101], v[10:17], v[214:221], v[98:101], v1, v186 op_sel_hi:[0,0,0]
	s_barrier
	s_add_i32 s66, s57, s30
	v_lshl_add_u64 v[178:179], s[24:25], 0, v[164:165]
	s_mov_b32 m0, s66
	ds_read_b128 v[198:201], v195 offset:16384
	ds_read_b128 v[206:209], v195 offset:18432
	ds_read_b128 v[202:205], v196 offset:16384
	ds_read_b128 v[210:213], v196 offset:18432
	ds_read_b128 v[214:217], v195 offset:20480
	ds_read_b128 v[222:225], v195 offset:22528
	ds_read_b128 v[218:221], v196 offset:20480
	ds_read_b128 v[226:229], v196 offset:22528
	global_load_lds_dwordx4 v[178:179], off
	s_add_i32 m0, s66, 0x2000
	s_add_u32 s66, s24, 0x40000
	v_lshl_add_u64 v[180:181], s[24:25], 0, v[168:169]
	s_addc_u32 s67, s25, 0
	s_add_i32 s72, s58, s30
	global_load_lds_dwordx4 v[180:181], off
	v_lshl_add_u64 v[182:183], s[66:67], 0, v[164:165]
	s_mov_b32 m0, s72
	v_lshl_add_u64 v[184:185], s[26:27], 0, v[166:167]
	global_load_lds_dwordx4 v[182:183], off
	v_lshl_add_u64 v[182:183], s[66:67], 0, v[168:169]
	s_add_i32 m0, s72, 0x2000
	s_nop 0
	global_load_lds_dwordx4 v[182:183], off
	v_lshl_add_u64 v[182:183], s[26:27], 0, v[162:163]
	s_mov_b32 m0, s21
	s_nop 0
	global_load_lds_dwordx4 v[182:183], off
	s_mov_b32 m0, s34
	s_nop 0
	global_load_lds_dwordx4 v[184:185], off
	s_waitcnt vmcnt(8)
	s_waitcnt lgkmcnt(0)
	s_barrier
	s_waitcnt lgkmcnt(0)
	v_mfma_scale_f32_16x16x128_f8f6f4 v[94:97], v[18:25], v[198:205], v[94:97], v1, v186 op_sel_hi:[0,0,0]
	v_mfma_scale_f32_16x16x128_f8f6f4 v[86:89], v[26:33], v[198:205], v[86:89], v1, v186 op_sel_hi:[0,0,0]
	v_mfma_scale_f32_16x16x128_f8f6f4 v[78:81], v[18:25], v[206:213], v[78:81], v1, v186 op_sel_hi:[0,0,0]
	v_mfma_scale_f32_16x16x128_f8f6f4 v[70:73], v[26:33], v[206:213], v[70:73], v1, v186 op_sel_hi:[0,0,0]
	v_mfma_scale_f32_16x16x128_f8f6f4 v[62:65], v[18:25], v[214:221], v[62:65], v1, v186 op_sel_hi:[0,0,0]
	v_mfma_scale_f32_16x16x128_f8f6f4 v[54:57], v[26:33], v[214:221], v[54:57], v1, v186 op_sel_hi:[0,0,0]
	v_mfma_scale_f32_16x16x128_f8f6f4 v[46:49], v[18:25], v[222:229], v[46:49], v1, v186 op_sel_hi:[0,0,0]
	v_mfma_scale_f32_16x16x128_f8f6f4 v[38:41], v[26:33], v[222:229], v[38:41], v1, v186 op_sel_hi:[0,0,0]
	v_mfma_scale_f32_16x16x128_f8f6f4 v[90:93], v[2:9], v[198:205], v[90:93], v1, v186 op_sel_hi:[0,0,0]
	v_mfma_scale_f32_16x16x128_f8f6f4 v[82:85], v[10:17], v[198:205], v[82:85], v1, v186 op_sel_hi:[0,0,0]
	v_mfma_scale_f32_16x16x128_f8f6f4 v[74:77], v[2:9], v[206:213], v[74:77], v1, v186 op_sel_hi:[0,0,0]
	v_mfma_scale_f32_16x16x128_f8f6f4 v[66:69], v[10:17], v[206:213], v[66:69], v1, v186 op_sel_hi:[0,0,0]
	v_mfma_scale_f32_16x16x128_f8f6f4 v[58:61], v[2:9], v[214:221], v[58:61], v1, v186 op_sel_hi:[0,0,0]
	v_mfma_scale_f32_16x16x128_f8f6f4 v[50:53], v[10:17], v[214:221], v[50:53], v1, v186 op_sel_hi:[0,0,0]
	v_mfma_scale_f32_16x16x128_f8f6f4 v[42:45], v[2:9], v[222:229], v[42:45], v1, v186 op_sel_hi:[0,0,0]
	v_mfma_scale_f32_16x16x128_f8f6f4 v[34:37], v[10:17], v[222:229], v[34:37], v1, v186 op_sel_hi:[0,0,0]
	s_barrier
; #define PG8_STAGE(bufoff, gbase, voff) do { _Pragma("unroll") for (int _i = 0; _i < 2; ++_i) \
;         __builtin_amdgcn_global_load_lds((const unsigned*)((const char*)(gbase) + (voff)[_i]), (PG8_LAS unsigned*)(lds + (bufoff) + ldsw + _i * 8192), 16, 0, 0); } while (0)
; #define PG8_LDA(dst, b, h) do { _Pragma("unroll") for (int m = 0; m < 4; ++m) _Pragma("unroll") for (int k = 0; k < 2; ++k) dst[m][k] = *(const PG8_LAS bf16x8*)(lds + PG8_SA(b, h) + aoff + m * 2048 + k * 1024); } while (0)
; #define PG8_LDB(dst, b, h) do { _Pragma("unroll") for (int n = 0; n < 2; ++n) _Pragma("unroll") for (int k = 0; k < 2; ++k) dst[n][k] = *(const PG8_LAS bf16x8*)(lds + PG8_SB(b, h) + boff + n * 2048 + k * 1024); } while (0)
; #define PG8_MMA(ai, bj, At, Bt) do { __builtin_amdgcn_s_setprio(1); _Pragma("unroll") for (int m = 0; m < 4; ++m) _Pragma("unroll") for (int n = 0; n < 2; ++n) _Pragma("unroll") for (int k = 0; k < 2; ++k) \
;         acc[ai][bj][m][n] = __builtin_amdgcn_mfma_f32_16x16x32_bf16(Bt[n][k], At[m][k], acc[ai][bj][m][n], 0, 0, 0); __builtin_amdgcn_s_setprio(0); } while (0)
; #define PG8_WAIT_V(n) asm volatile("s_waitcnt vmcnt(" #n ")" ::: "memory")
; #define PG8_WAIT_L(n) asm volatile("s_waitcnt lgkmcnt(" #n ")" ::: "memory")
; #define PG8_BAR __builtin_amdgcn_s_barrier()
; #define PG8_SCHED __builtin_amdgcn_sched_barrier(0)
; #define PG8_STAGE(bufoff, gbase, voff) do { _Pragma("unroll") for (int _i = 0; _i < 2; ++_i) \
;         __builtin_amdgcn_global_load_lds((const unsigned*)((const char*)(gbase) + (voff)[_i]), (PG8_LAS unsigned*)(lds + (bufoff) + ldsw + _i * 8192), 16, 0, 0); } while (0)
; #define PG8_BAR __builtin_amdgcn_s_barrier()
; template <class Epi, class Sched, bool ALIGN_EPI = false>
; __device__ __forceinline__ void gemm_phase8(PG8_LAS unsigned char* lds, const Gemm g, const Sched& S, const Epi& E) {
;     ...
;             PG8_LDB(B0, 1, 0); PG8_LDB(B1, 1, 1); PG8_SCHED; PG8_LDA(At, 1, 0); PG8_STAGE(PG8_SA(0, 1), a2 + hstepA, voffA);
;             PG8_WAIT_V(8); PG8_WAIT_L(0); PG8_BAR; PG8_MMA(0, 0, At, B0); PG8_MMA(0, 1, At, B1); PG8_BAR; PG8_SCHED;
;             PG8_LDA(At, 1, 1); PG8_STAGE(PG8_SB(1, 0), b3, voffB); PG8_STAGE(PG8_SB(1, 1), b3 + hstepB, voffB); PG8_STAGE(PG8_SA(1, 0), a3, voffA);
;             PG8_WAIT_V(8); PG8_WAIT_L(0); PG8_BAR; PG8_MMA(1, 0, At, B0); PG8_MMA(1, 1, At, B1); PG8_BAR; PG8_SCHED;
;         }
	s_add_i32 s66, 0, 0x18000
	s_add_i32 s67, 0, 0x1c000
	v_add_u32_e32 v6, s66, v187
	v_add_u32_e32 v14, s66, v188
	v_add_u32_e32 v22, s67, v187
	v_add_u32_e32 v30, s67, v188
	ds_read_b128 v[2:5], v6
	ds_read_b128 v[10:13], v6 offset:2048
	ds_read_b128 v[6:9], v14
	ds_read_b128 v[14:17], v14 offset:2048
	ds_read_b128 v[18:21], v22
	ds_read_b128 v[26:29], v22 offset:2048
	ds_read_b128 v[22:25], v30
	ds_read_b128 v[30:33], v30 offset:2048
	s_add_u32 s26, s26, 0x40000
	s_addc_u32 s27, s27, 0
	s_mov_b32 m0, s35
	v_lshl_add_u64 v[230:231], s[26:27], 0, v[162:163]
	ds_read_b128 v[198:201], v195 offset:32768
	ds_read_b128 v[206:209], v195 offset:34816
	ds_read_b128 v[202:205], v196 offset:32768
	ds_read_b128 v[210:213], v196 offset:34816
	ds_read_b128 v[214:217], v195 offset:36864
	ds_read_b128 v[222:225], v195 offset:38912
	ds_read_b128 v[218:221], v196 offset:36864
	ds_read_b128 v[226:229], v196 offset:38912
	global_load_lds_dwordx4 v[230:231], off
	v_lshl_add_u64 v[230:231], s[26:27], 0, v[166:167]
	s_mov_b32 m0, s52
	s_nop 0
	global_load_lds_dwordx4 v[230:231], off
	s_waitcnt vmcnt(8)
	s_waitcnt lgkmcnt(0)
	s_barrier
	s_waitcnt lgkmcnt(0)
	v_mfma_scale_f32_16x16x128_f8f6f4 v[158:161], v[2:9], v[198:205], v[158:161], v1, v186 op_sel_hi:[0,0,0]
	v_mfma_scale_f32_16x16x128_f8f6f4 v[150:153], v[10:17], v[198:205], v[150:153], v1, v186 op_sel_hi:[0,0,0]
	v_mfma_scale_f32_16x16x128_f8f6f4 v[142:145], v[2:9], v[206:213], v[142:145], v1, v186 op_sel_hi:[0,0,0]
	v_mfma_scale_f32_16x16x128_f8f6f4 v[134:137], v[10:17], v[206:213], v[134:137], v1, v186 op_sel_hi:[0,0,0]
	v_mfma_scale_f32_16x16x128_f8f6f4 v[126:129], v[2:9], v[214:221], v[126:129], v1, v186 op_sel_hi:[0,0,0]
	v_mfma_scale_f32_16x16x128_f8f6f4 v[118:121], v[10:17], v[214:221], v[118:121], v1, v186 op_sel_hi:[0,0,0]
	v_mfma_scale_f32_16x16x128_f8f6f4 v[110:113], v[2:9], v[222:229], v[110:113], v1, v186 op_sel_hi:[0,0,0]
	v_mfma_scale_f32_16x16x128_f8f6f4 v[102:105], v[10:17], v[222:229], v[102:105], v1, v186 op_sel_hi:[0,0,0]
	v_mfma_scale_f32_16x16x128_f8f6f4 v[154:157], v[18:25], v[198:205], v[154:157], v1, v186 op_sel_hi:[0,0,0]
	v_mfma_scale_f32_16x16x128_f8f6f4 v[146:149], v[26:33], v[198:205], v[146:149], v1, v186 op_sel_hi:[0,0,0]
	v_mfma_scale_f32_16x16x128_f8f6f4 v[138:141], v[18:25], v[206:213], v[138:141], v1, v186 op_sel_hi:[0,0,0]
	v_mfma_scale_f32_16x16x128_f8f6f4 v[130:133], v[26:33], v[206:213], v[130:133], v1, v186 op_sel_hi:[0,0,0]
	v_mfma_scale_f32_16x16x128_f8f6f4 v[122:125], v[18:25], v[214:221], v[122:125], v1, v186 op_sel_hi:[0,0,0]
	v_mfma_scale_f32_16x16x128_f8f6f4 v[114:117], v[26:33], v[214:221], v[114:117], v1, v186 op_sel_hi:[0,0,0]
	v_mfma_scale_f32_16x16x128_f8f6f4 v[106:109], v[18:25], v[222:229], v[106:109], v1, v186 op_sel_hi:[0,0,0]
	v_mfma_scale_f32_16x16x128_f8f6f4 v[98:101], v[26:33], v[222:229], v[98:101], v1, v186 op_sel_hi:[0,0,0]
	s_barrier
	s_add_i32 s26, s66, s30
	v_lshl_add_u64 v[178:179], v[178:179], 0, s[8:9]
	s_mov_b32 m0, s26
	ds_read_b128 v[198:201], v195 offset:49152
	ds_read_b128 v[206:209], v195 offset:51200
	ds_read_b128 v[202:205], v196 offset:49152
	ds_read_b128 v[210:213], v196 offset:51200
	ds_read_b128 v[214:217], v195 offset:53248
	ds_read_b128 v[222:225], v195 offset:55296
	ds_read_b128 v[218:221], v196 offset:53248
	ds_read_b128 v[226:229], v196 offset:55296
	global_load_lds_dwordx4 v[178:179], off
	s_add_i32 m0, s26, 0x2000
	s_add_u32 s24, s24, 0x40080
	v_lshl_add_u64 v[178:179], v[180:181], 0, s[8:9]
	s_addc_u32 s25, s25, 0
	s_add_i32 s26, s67, s30
	global_load_lds_dwordx4 v[178:179], off
	v_lshl_add_u64 v[178:179], s[24:25], 0, v[164:165]
	s_mov_b32 m0, s26
	s_nop 0
	global_load_lds_dwordx4 v[178:179], off
	v_lshl_add_u64 v[178:179], s[24:25], 0, v[168:169]
	s_add_i32 m0, s26, 0x2000
	s_nop 0
	global_load_lds_dwordx4 v[178:179], off
	v_lshl_add_u64 v[178:179], v[182:183], 0, s[8:9]
	s_mov_b32 m0, s55
	s_nop 0
	global_load_lds_dwordx4 v[178:179], off
	v_lshl_add_u64 v[178:179], v[184:185], 0, s[8:9]
	s_mov_b32 m0, s56
	s_nop 0
	global_load_lds_dwordx4 v[178:179], off
	s_waitcnt vmcnt(8)
	s_waitcnt lgkmcnt(0)
	s_barrier
	s_waitcnt lgkmcnt(0)
	v_mfma_scale_f32_16x16x128_f8f6f4 v[94:97], v[2:9], v[198:205], v[94:97], v1, v186 op_sel_hi:[0,0,0]
	v_mfma_scale_f32_16x16x128_f8f6f4 v[86:89], v[10:17], v[198:205], v[86:89], v1, v186 op_sel_hi:[0,0,0]
	v_mfma_scale_f32_16x16x128_f8f6f4 v[78:81], v[2:9], v[206:213], v[78:81], v1, v186 op_sel_hi:[0,0,0]
	v_mfma_scale_f32_16x16x128_f8f6f4 v[70:73], v[10:17], v[206:213], v[70:73], v1, v186 op_sel_hi:[0,0,0]
	v_mfma_scale_f32_16x16x128_f8f6f4 v[62:65], v[2:9], v[214:221], v[62:65], v1, v186 op_sel_hi:[0,0,0]
	v_mfma_scale_f32_16x16x128_f8f6f4 v[54:57], v[10:17], v[214:221], v[54:57], v1, v186 op_sel_hi:[0,0,0]
	v_mfma_scale_f32_16x16x128_f8f6f4 v[46:49], v[2:9], v[222:229], v[46:49], v1, v186 op_sel_hi:[0,0,0]
	v_mfma_scale_f32_16x16x128_f8f6f4 v[38:41], v[10:17], v[222:229], v[38:41], v1, v186 op_sel_hi:[0,0,0]
	v_mfma_scale_f32_16x16x128_f8f6f4 v[90:93], v[18:25], v[198:205], v[90:93], v1, v186 op_sel_hi:[0,0,0]
	v_mfma_scale_f32_16x16x128_f8f6f4 v[82:85], v[26:33], v[198:205], v[82:85], v1, v186 op_sel_hi:[0,0,0]
	v_mfma_scale_f32_16x16x128_f8f6f4 v[74:77], v[18:25], v[206:213], v[74:77], v1, v186 op_sel_hi:[0,0,0]
	v_mfma_scale_f32_16x16x128_f8f6f4 v[66:69], v[26:33], v[206:213], v[66:69], v1, v186 op_sel_hi:[0,0,0]
	v_mfma_scale_f32_16x16x128_f8f6f4 v[58:61], v[18:25], v[214:221], v[58:61], v1, v186 op_sel_hi:[0,0,0]
	v_mfma_scale_f32_16x16x128_f8f6f4 v[50:53], v[26:33], v[214:221], v[50:53], v1, v186 op_sel_hi:[0,0,0]
	v_mfma_scale_f32_16x16x128_f8f6f4 v[42:45], v[18:25], v[222:229], v[42:45], v1, v186 op_sel_hi:[0,0,0]
	v_mfma_scale_f32_16x16x128_f8f6f4 v[34:37], v[26:33], v[222:229], v[34:37], v1, v186 op_sel_hi:[0,0,0]
	s_barrier
	s_add_i32 s65, s65, 2
	s_add_u32 s22, s22, 0x100
	s_addc_u32 s23, s23, 0
	s_add_u32 s63, s63, 0x100
	s_addc_u32 s64, s64, 0
	s_cmp_gt_u32 s65, 13
	s_cbranch_scc0 .LBB0_325
	s_and_b64 vcc, exec, s[10:11]
	s_cbranch_vccz .LBB0_328
	s_barrier

; #define PG8_STAGE(bufoff, gbase, voff) do { _Pragma("unroll") for (int _i = 0; _i < 2; ++_i) \
;         __builtin_amdgcn_global_load_lds((const unsigned*)((const char*)(gbase) + (voff)[_i]), (PG8_LAS unsigned*)(lds + (bufoff) + ldsw + _i * 8192), 16, 0, 0); } while (0)
; #define PG8_LDA(dst, b, h) do { _Pragma("unroll") for (int m = 0; m < 4; ++m) _Pragma("unroll") for (int k = 0; k < 2; ++k) dst[m][k] = *(const PG8_LAS bf16x8*)(lds + PG8_SA(b, h) + aoff + m * 2048 + k * 1024); } while (0)
; #define PG8_LDB(dst, b, h) do { _Pragma("unroll") for (int n = 0; n < 2; ++n) _Pragma("unroll") for (int k = 0; k < 2; ++k) dst[n][k] = *(const PG8_LAS bf16x8*)(lds + PG8_SB(b, h) + boff + n * 2048 + k * 1024); } while (0)
; #define PG8_MMA(ai, bj, At, Bt) do { __builtin_amdgcn_s_setprio(1); _Pragma("unroll") for (int m = 0; m < 4; ++m) _Pragma("unroll") for (int n = 0; n < 2; ++n) _Pragma("unroll") for (int k = 0; k < 2; ++k) \
;         acc[ai][bj][m][n] = __builtin_amdgcn_mfma_f32_16x16x32_bf16(Bt[n][k], At[m][k], acc[ai][bj][m][n], 0, 0, 0); __builtin_amdgcn_s_setprio(0); } while (0)
; #define PG8_WAIT_V(n) asm volatile("s_waitcnt vmcnt(" #n ")" ::: "memory")
; #define PG8_WAIT_L(n) asm volatile("s_waitcnt lgkmcnt(" #n ")" ::: "memory")
; #define PG8_BAR __builtin_amdgcn_s_barrier()
; template <class Epi, class Sched, bool ALIGN_EPI = false>
; __device__ __forceinline__ void gemm_phase8(PG8_LAS unsigned char* lds, const Gemm g, const Sched& S, const Epi& E) {
;     ...
;             const bool last = (t == nt - 2);
;             const char* a1 = cA + (size_t)(t + 1) * kstep;
;             const char* a2 = last ? nA : cA + (size_t)(t + 2) * kstep; const char* b2 = last ? nB : cB + (size_t)(t + 2) * kstep;
;             const char* a3 = a2 + kstep; const char* b3 = b2 + kstep;
;             if (last && has_next) S.a_ready(nxt);
;             PG8_LDB(B0, 0, 0); PG8_LDB(B1, 0, 1); PG8_SCHED; PG8_LDA(At, 0, 0); PG8_STAGE(PG8_SA(1, 1), a1 + hstepA, voffA);
;             PG8_WAIT_V(8); PG8_WAIT_L(0); PG8_BAR; PG8_MMA(0, 0, At, B0); PG8_MMA(0, 1, At, B1); PG8_BAR; PG8_SCHED;
;             PG8_LDA(At, 0, 1); PG8_STAGE(PG8_SB(0, 0), b2, voffB); PG8_STAGE(PG8_SB(0, 1), b2 + hstepB, voffB); PG8_STAGE(PG8_SA(0, 0), a2, voffA);
;             PG8_WAIT_V(8); PG8_WAIT_L(0); PG8_BAR; PG8_MMA(1, 0, At, B0); PG8_MMA(1, 1, At, B1); PG8_BAR; PG8_SCHED;
.LBB0_502:
	ds_read_b128 v[18:21], v187
	ds_read_b128 v[26:29], v187 offset:2048
	ds_read_b128 v[22:25], v188
	ds_read_b128 v[30:33], v188 offset:2048
	ds_read_b128 v[2:5], v189
	ds_read_b128 v[10:13], v189 offset:2048
	ds_read_b128 v[6:9], v190
	ds_read_b128 v[14:17], v190 offset:2048
	s_add_i32 s84, s34, 2
	s_add_u32 s30, s28, 0xfff50080
	s_addc_u32 s31, s29, -1
	s_cmp_eq_u32 s81, s34
	s_cselect_b32 s34, s20, s30
	s_cselect_b32 s35, s21, s31
	s_cselect_b32 s31, s23, s83
	s_cselect_b32 s30, s22, s82
	v_lshl_add_u64 v[218:219], s[28:29], 0, v[170:171]
	s_add_i32 m0, s54, 0xc000
	ds_read_b128 v[174:177], v191
	ds_read_b128 v[194:197], v191 offset:2048
	ds_read_b128 v[178:181], v192
	ds_read_b128 v[198:201], v192 offset:2048
	ds_read_b128 v[202:205], v191 offset:4096
	ds_read_b128 v[210:213], v191 offset:6144
	ds_read_b128 v[206:209], v192 offset:4096
	ds_read_b128 v[214:217], v192 offset:6144
	global_load_lds_dwordx4 v[218:219], off
	v_lshl_add_u64 v[218:219], s[28:29], 0, v[172:173]
	s_add_i32 m0, s54, 0xe000
	s_nop 0
	global_load_lds_dwordx4 v[218:219], off
	s_waitcnt vmcnt(8)
	s_waitcnt lgkmcnt(0)
	s_barrier
	s_waitcnt lgkmcnt(0)
	v_mfma_scale_f32_16x16x128_f8f6f4 v[158:161], v[18:25], v[174:181], v[158:161], v1, v182 op_sel_hi:[0,0,0]
	v_mfma_scale_f32_16x16x128_f8f6f4 v[154:157], v[26:33], v[174:181], v[154:157], v1, v182 op_sel_hi:[0,0,0]
	v_mfma_scale_f32_16x16x128_f8f6f4 v[142:145], v[18:25], v[194:201], v[142:145], v1, v182 op_sel_hi:[0,0,0]
	v_mfma_scale_f32_16x16x128_f8f6f4 v[138:141], v[26:33], v[194:201], v[138:141], v1, v182 op_sel_hi:[0,0,0]
	v_mfma_scale_f32_16x16x128_f8f6f4 v[126:129], v[18:25], v[202:209], v[126:129], v1, v182 op_sel_hi:[0,0,0]
	v_mfma_scale_f32_16x16x128_f8f6f4 v[122:125], v[26:33], v[202:209], v[122:125], v1, v182 op_sel_hi:[0,0,0]
	v_mfma_scale_f32_16x16x128_f8f6f4 v[110:113], v[18:25], v[210:217], v[110:113], v1, v182 op_sel_hi:[0,0,0]
	v_mfma_scale_f32_16x16x128_f8f6f4 v[106:109], v[26:33], v[210:217], v[106:109], v1, v182 op_sel_hi:[0,0,0]
	v_mfma_scale_f32_16x16x128_f8f6f4 v[150:153], v[2:9], v[174:181], v[150:153], v1, v182 op_sel_hi:[0,0,0]
	v_mfma_scale_f32_16x16x128_f8f6f4 v[146:149], v[10:17], v[174:181], v[146:149], v1, v182 op_sel_hi:[0,0,0]
	v_mfma_scale_f32_16x16x128_f8f6f4 v[134:137], v[2:9], v[194:201], v[134:137], v1, v182 op_sel_hi:[0,0,0]
	v_mfma_scale_f32_16x16x128_f8f6f4 v[130:133], v[10:17], v[194:201], v[130:133], v1, v182 op_sel_hi:[0,0,0]
	v_mfma_scale_f32_16x16x128_f8f6f4 v[118:121], v[2:9], v[202:209], v[118:121], v1, v182 op_sel_hi:[0,0,0]
	v_mfma_scale_f32_16x16x128_f8f6f4 v[114:117], v[10:17], v[202:209], v[114:117], v1, v182 op_sel_hi:[0,0,0]
	v_mfma_scale_f32_16x16x128_f8f6f4 v[102:105], v[2:9], v[210:217], v[102:105], v1, v182 op_sel_hi:[0,0,0]
	v_mfma_scale_f32_16x16x128_f8f6f4 v[98:101], v[10:17], v[210:217], v[98:101], v1, v182 op_sel_hi:[0,0,0]
	s_barrier
	s_add_i32 s85, s65, s53
	v_lshl_add_u64 v[174:175], s[30:31], 0, v[164:165]
	s_mov_b32 m0, s85
	ds_read_b128 v[194:197], v191 offset:16384
	ds_read_b128 v[202:205], v191 offset:18432
	ds_read_b128 v[198:201], v192 offset:16384
	ds_read_b128 v[206:209], v192 offset:18432
	ds_read_b128 v[210:213], v191 offset:20480
	ds_read_b128 v[218:221], v191 offset:22528
	ds_read_b128 v[214:217], v192 offset:20480
	ds_read_b128 v[222:225], v192 offset:22528
	global_load_lds_dwordx4 v[174:175], off
	s_add_i32 m0, s85, 0x2000
	s_add_u32 s88, s30, 0xb0000
	v_lshl_add_u64 v[176:177], s[30:31], 0, v[168:169]
	s_addc_u32 s89, s31, 0
	s_add_i32 s85, s66, s53
	global_load_lds_dwordx4 v[176:177], off
	v_lshl_add_u64 v[178:179], s[88:89], 0, v[164:165]
	s_mov_b32 m0, s85
	v_lshl_add_u64 v[180:181], s[34:35], 0, v[166:167]
	global_load_lds_dwordx4 v[178:179], off
	v_lshl_add_u64 v[178:179], s[88:89], 0, v[168:169]
	s_add_i32 m0, s85, 0x2000
	s_nop 0
	global_load_lds_dwordx4 v[178:179], off
	v_lshl_add_u64 v[178:179], s[34:35], 0, v[162:163]
	s_mov_b32 m0, s54
	s_nop 0
	global_load_lds_dwordx4 v[178:179], off
	s_mov_b32 m0, s55
	s_nop 0
	global_load_lds_dwordx4 v[180:181], off
	s_waitcnt vmcnt(8)
	s_waitcnt lgkmcnt(0)
	s_barrier
	s_waitcnt lgkmcnt(0)
	v_mfma_scale_f32_16x16x128_f8f6f4 v[94:97], v[18:25], v[194:201], v[94:97], v1, v182 op_sel_hi:[0,0,0]
	v_mfma_scale_f32_16x16x128_f8f6f4 v[90:93], v[26:33], v[194:201], v[90:93], v1, v182 op_sel_hi:[0,0,0]
	v_mfma_scale_f32_16x16x128_f8f6f4 v[78:81], v[18:25], v[202:209], v[78:81], v1, v182 op_sel_hi:[0,0,0]
	v_mfma_scale_f32_16x16x128_f8f6f4 v[74:77], v[26:33], v[202:209], v[74:77], v1, v182 op_sel_hi:[0,0,0]
	v_mfma_scale_f32_16x16x128_f8f6f4 v[62:65], v[18:25], v[210:217], v[62:65], v1, v182 op_sel_hi:[0,0,0]
	v_mfma_scale_f32_16x16x128_f8f6f4 v[58:61], v[26:33], v[210:217], v[58:61], v1, v182 op_sel_hi:[0,0,0]
	v_mfma_scale_f32_16x16x128_f8f6f4 v[46:49], v[18:25], v[218:225], v[46:49], v1, v182 op_sel_hi:[0,0,0]
	v_mfma_scale_f32_16x16x128_f8f6f4 v[42:45], v[26:33], v[218:225], v[42:45], v1, v182 op_sel_hi:[0,0,0]
	v_mfma_scale_f32_16x16x128_f8f6f4 v[86:89], v[2:9], v[194:201], v[86:89], v1, v182 op_sel_hi:[0,0,0]
	v_mfma_scale_f32_16x16x128_f8f6f4 v[82:85], v[10:17], v[194:201], v[82:85], v1, v182 op_sel_hi:[0,0,0]
	v_mfma_scale_f32_16x16x128_f8f6f4 v[70:73], v[2:9], v[202:209], v[70:73], v1, v182 op_sel_hi:[0,0,0]
	v_mfma_scale_f32_16x16x128_f8f6f4 v[66:69], v[10:17], v[202:209], v[66:69], v1, v182 op_sel_hi:[0,0,0]
	v_mfma_scale_f32_16x16x128_f8f6f4 v[54:57], v[2:9], v[210:217], v[54:57], v1, v182 op_sel_hi:[0,0,0]
	v_mfma_scale_f32_16x16x128_f8f6f4 v[50:53], v[10:17], v[210:217], v[50:53], v1, v182 op_sel_hi:[0,0,0]
	v_mfma_scale_f32_16x16x128_f8f6f4 v[38:41], v[2:9], v[218:225], v[38:41], v1, v182 op_sel_hi:[0,0,0]
	v_mfma_scale_f32_16x16x128_f8f6f4 v[34:37], v[10:17], v[218:225], v[34:37], v1, v182 op_sel_hi:[0,0,0]
	s_barrier
; #define PG8_STAGE(bufoff, gbase, voff) do { _Pragma("unroll") for (int _i = 0; _i < 2; ++_i) \
;         __builtin_amdgcn_global_load_lds((const unsigned*)((const char*)(gbase) + (voff)[_i]), (PG8_LAS unsigned*)(lds + (bufoff) + ldsw + _i * 8192), 16, 0, 0); } while (0)
; #define PG8_LDA(dst, b, h) do { _Pragma("unroll") for (int m = 0; m < 4; ++m) _Pragma("unroll") for (int k = 0; k < 2; ++k) dst[m][k] = *(const PG8_LAS bf16x8*)(lds + PG8_SA(b, h) + aoff + m * 2048 + k * 1024); } while (0)
; #define PG8_LDB(dst, b, h) do { _Pragma("unroll") for (int n = 0; n < 2; ++n) _Pragma("unroll") for (int k = 0; k < 2; ++k) dst[n][k] = *(const PG8_LAS bf16x8*)(lds + PG8_SB(b, h) + boff + n * 2048 + k * 1024); } while (0)
; #define PG8_MMA(ai, bj, At, Bt) do { __builtin_amdgcn_s_setprio(1); _Pragma("unroll") for (int m = 0; m < 4; ++m) _Pragma("unroll") for (int n = 0; n < 2; ++n) _Pragma("unroll") for (int k = 0; k < 2; ++k) \
;         acc[ai][bj][m][n] = __builtin_amdgcn_mfma_f32_16x16x32_bf16(Bt[n][k], At[m][k], acc[ai][bj][m][n], 0, 0, 0); __builtin_amdgcn_s_setprio(0); } while (0)
; #define PG8_WAIT_V(n) asm volatile("s_waitcnt vmcnt(" #n ")" ::: "memory")
; #define PG8_WAIT_L(n) asm volatile("s_waitcnt lgkmcnt(" #n ")" ::: "memory")
; #define PG8_BAR __builtin_amdgcn_s_barrier()
; #define PG8_SCHED __builtin_amdgcn_sched_barrier(0)
; #define PG8_STAGE(bufoff, gbase, voff) do { _Pragma("unroll") for (int _i = 0; _i < 2; ++_i) \
;         __builtin_amdgcn_global_load_lds((const unsigned*)((const char*)(gbase) + (voff)[_i]), (PG8_LAS unsigned*)(lds + (bufoff) + ldsw + _i * 8192), 16, 0, 0); } while (0)
; #define PG8_BAR __builtin_amdgcn_s_barrier()
; template <class Epi, class Sched, bool ALIGN_EPI = false>
; __device__ __forceinline__ void gemm_phase8(PG8_LAS unsigned char* lds, const Gemm g, const Sched& S, const Epi& E) {
;     ...
;             PG8_LDB(B0, 1, 0); PG8_LDB(B1, 1, 1); PG8_SCHED; PG8_LDA(At, 1, 0); PG8_STAGE(PG8_SA(0, 1), a2 + hstepA, voffA);
;             PG8_WAIT_V(8); PG8_WAIT_L(0); PG8_BAR; PG8_MMA(0, 0, At, B0); PG8_MMA(0, 1, At, B1); PG8_BAR; PG8_SCHED;
;             PG8_LDA(At, 1, 1); PG8_STAGE(PG8_SB(1, 0), b3, voffB); PG8_STAGE(PG8_SB(1, 1), b3 + hstepB, voffB); PG8_STAGE(PG8_SA(1, 0), a3, voffA);
;             PG8_WAIT_V(8); PG8_WAIT_L(0); PG8_BAR; PG8_MMA(1, 0, At, B0); PG8_MMA(1, 1, At, B1); PG8_BAR; PG8_SCHED;
;         }
	s_add_i32 s85, 0, 0x18000
	s_add_i32 s88, 0, 0x1c000
	v_add_u32_e32 v6, s85, v184
	v_add_u32_e32 v14, s85, v185
	v_add_u32_e32 v22, s88, v184
	v_add_u32_e32 v30, s88, v185
	ds_read_b128 v[2:5], v6
	ds_read_b128 v[10:13], v6 offset:2048
	ds_read_b128 v[6:9], v14
	ds_read_b128 v[14:17], v14 offset:2048
	ds_read_b128 v[18:21], v22
	ds_read_b128 v[26:29], v22 offset:2048
	ds_read_b128 v[22:25], v30
	ds_read_b128 v[30:33], v30 offset:2048
	s_add_u32 s34, s34, 0xb0000
	s_addc_u32 s35, s35, 0
	s_mov_b32 m0, s56
	v_lshl_add_u64 v[226:227], s[34:35], 0, v[162:163]
	ds_read_b128 v[194:197], v191 offset:32768
	ds_read_b128 v[202:205], v191 offset:34816
	ds_read_b128 v[198:201], v192 offset:32768
	ds_read_b128 v[206:209], v192 offset:34816
	ds_read_b128 v[210:213], v191 offset:36864
	ds_read_b128 v[218:221], v191 offset:38912
	ds_read_b128 v[214:217], v192 offset:36864
	ds_read_b128 v[222:225], v192 offset:38912
	global_load_lds_dwordx4 v[226:227], off
	v_lshl_add_u64 v[226:227], s[34:35], 0, v[166:167]
	s_mov_b32 m0, s57
	s_nop 0
	global_load_lds_dwordx4 v[226:227], off
	s_waitcnt vmcnt(8)
	s_waitcnt lgkmcnt(0)
	s_barrier
	s_waitcnt lgkmcnt(0)
	v_mfma_scale_f32_16x16x128_f8f6f4 v[158:161], v[2:9], v[194:201], v[158:161], v1, v182 op_sel_hi:[0,0,0]
	v_mfma_scale_f32_16x16x128_f8f6f4 v[154:157], v[10:17], v[194:201], v[154:157], v1, v182 op_sel_hi:[0,0,0]
	v_mfma_scale_f32_16x16x128_f8f6f4 v[142:145], v[2:9], v[202:209], v[142:145], v1, v182 op_sel_hi:[0,0,0]
	v_mfma_scale_f32_16x16x128_f8f6f4 v[138:141], v[10:17], v[202:209], v[138:141], v1, v182 op_sel_hi:[0,0,0]
	v_mfma_scale_f32_16x16x128_f8f6f4 v[126:129], v[2:9], v[210:217], v[126:129], v1, v182 op_sel_hi:[0,0,0]
	v_mfma_scale_f32_16x16x128_f8f6f4 v[122:125], v[10:17], v[210:217], v[122:125], v1, v182 op_sel_hi:[0,0,0]
	v_mfma_scale_f32_16x16x128_f8f6f4 v[110:113], v[2:9], v[218:225], v[110:113], v1, v182 op_sel_hi:[0,0,0]
	v_mfma_scale_f32_16x16x128_f8f6f4 v[106:109], v[10:17], v[218:225], v[106:109], v1, v182 op_sel_hi:[0,0,0]
	v_mfma_scale_f32_16x16x128_f8f6f4 v[150:153], v[18:25], v[194:201], v[150:153], v1, v182 op_sel_hi:[0,0,0]
	v_mfma_scale_f32_16x16x128_f8f6f4 v[146:149], v[26:33], v[194:201], v[146:149], v1, v182 op_sel_hi:[0,0,0]
	v_mfma_scale_f32_16x16x128_f8f6f4 v[134:137], v[18:25], v[202:209], v[134:137], v1, v182 op_sel_hi:[0,0,0]
	v_mfma_scale_f32_16x16x128_f8f6f4 v[130:133], v[26:33], v[202:209], v[130:133], v1, v182 op_sel_hi:[0,0,0]
	v_mfma_scale_f32_16x16x128_f8f6f4 v[118:121], v[18:25], v[210:217], v[118:121], v1, v182 op_sel_hi:[0,0,0]
	v_mfma_scale_f32_16x16x128_f8f6f4 v[114:117], v[26:33], v[210:217], v[114:117], v1, v182 op_sel_hi:[0,0,0]
	v_mfma_scale_f32_16x16x128_f8f6f4 v[102:105], v[18:25], v[218:225], v[102:105], v1, v182 op_sel_hi:[0,0,0]
	v_mfma_scale_f32_16x16x128_f8f6f4 v[98:101], v[26:33], v[218:225], v[98:101], v1, v182 op_sel_hi:[0,0,0]
	s_barrier
	s_add_i32 s34, s85, s53
	v_lshl_add_u64 v[174:175], v[174:175], 0, s[12:13]
	s_mov_b32 m0, s34
	ds_read_b128 v[194:197], v191 offset:49152
	ds_read_b128 v[202:205], v191 offset:51200
	ds_read_b128 v[198:201], v192 offset:49152
	ds_read_b128 v[206:209], v192 offset:51200
	ds_read_b128 v[210:213], v191 offset:53248
	ds_read_b128 v[218:221], v191 offset:55296
	ds_read_b128 v[214:217], v192 offset:53248
	ds_read_b128 v[222:225], v192 offset:55296
	global_load_lds_dwordx4 v[174:175], off
	s_add_i32 m0, s34, 0x2000
	s_add_u32 s30, s30, 0xb0080
	v_lshl_add_u64 v[174:175], v[176:177], 0, s[12:13]
	s_addc_u32 s31, s31, 0
	s_add_i32 s34, s88, s53
	global_load_lds_dwordx4 v[174:175], off
	v_lshl_add_u64 v[174:175], s[30:31], 0, v[164:165]
	s_mov_b32 m0, s34
	s_nop 0
	global_load_lds_dwordx4 v[174:175], off
	v_lshl_add_u64 v[174:175], s[30:31], 0, v[168:169]
	s_add_i32 m0, s34, 0x2000
	s_nop 0
	global_load_lds_dwordx4 v[174:175], off
	v_lshl_add_u64 v[174:175], v[178:179], 0, s[12:13]
	s_mov_b32 m0, s63
	s_nop 0
	global_load_lds_dwordx4 v[174:175], off
	v_lshl_add_u64 v[174:175], v[180:181], 0, s[12:13]
	s_mov_b32 m0, s64
	s_nop 0
	global_load_lds_dwordx4 v[174:175], off
	s_waitcnt vmcnt(8)
	s_waitcnt lgkmcnt(0)
	s_barrier
	s_waitcnt lgkmcnt(0)
	v_mfma_scale_f32_16x16x128_f8f6f4 v[94:97], v[2:9], v[194:201], v[94:97], v1, v182 op_sel_hi:[0,0,0]
	v_mfma_scale_f32_16x16x128_f8f6f4 v[90:93], v[10:17], v[194:201], v[90:93], v1, v182 op_sel_hi:[0,0,0]
	v_mfma_scale_f32_16x16x128_f8f6f4 v[78:81], v[2:9], v[202:209], v[78:81], v1, v182 op_sel_hi:[0,0,0]
	v_mfma_scale_f32_16x16x128_f8f6f4 v[74:77], v[10:17], v[202:209], v[74:77], v1, v182 op_sel_hi:[0,0,0]
	v_mfma_scale_f32_16x16x128_f8f6f4 v[62:65], v[2:9], v[210:217], v[62:65], v1, v182 op_sel_hi:[0,0,0]
	v_mfma_scale_f32_16x16x128_f8f6f4 v[58:61], v[10:17], v[210:217], v[58:61], v1, v182 op_sel_hi:[0,0,0]
	v_mfma_scale_f32_16x16x128_f8f6f4 v[46:49], v[2:9], v[218:225], v[46:49], v1, v182 op_sel_hi:[0,0,0]
	v_mfma_scale_f32_16x16x128_f8f6f4 v[42:45], v[10:17], v[218:225], v[42:45], v1, v182 op_sel_hi:[0,0,0]
	v_mfma_scale_f32_16x16x128_f8f6f4 v[86:89], v[18:25], v[194:201], v[86:89], v1, v182 op_sel_hi:[0,0,0]
	v_mfma_scale_f32_16x16x128_f8f6f4 v[82:85], v[26:33], v[194:201], v[82:85], v1, v182 op_sel_hi:[0,0,0]
	v_mfma_scale_f32_16x16x128_f8f6f4 v[70:73], v[18:25], v[202:209], v[70:73], v1, v182 op_sel_hi:[0,0,0]
	v_mfma_scale_f32_16x16x128_f8f6f4 v[66:69], v[26:33], v[202:209], v[66:69], v1, v182 op_sel_hi:[0,0,0]
	v_mfma_scale_f32_16x16x128_f8f6f4 v[54:57], v[18:25], v[210:217], v[54:57], v1, v182 op_sel_hi:[0,0,0]
	v_mfma_scale_f32_16x16x128_f8f6f4 v[50:53], v[26:33], v[210:217], v[50:53], v1, v182 op_sel_hi:[0,0,0]
	v_mfma_scale_f32_16x16x128_f8f6f4 v[38:41], v[18:25], v[218:225], v[38:41], v1, v182 op_sel_hi:[0,0,0]
	v_mfma_scale_f32_16x16x128_f8f6f4 v[34:37], v[26:33], v[218:225], v[34:37], v1, v182 op_sel_hi:[0,0,0]
	s_barrier
	s_add_u32 s28, s28, 0x100
	s_addc_u32 s29, s29, 0
	s_add_u32 s82, s82, 0x100
	s_addc_u32 s83, s83, 0
	s_cmp_ge_u32 s84, s25
	s_mov_b32 s34, s84
	s_cbranch_scc0 .LBB0_502
	s_and_b64 vcc, exec, s[14:15]
	s_cbranch_vccz .LBB0_505
	s_barrier

; #define PG8_STAGE(bufoff, gbase, voff) do { _Pragma("unroll") for (int _i = 0; _i < 2; ++_i) \
;         __builtin_amdgcn_global_load_lds((const unsigned*)((const char*)(gbase) + (voff)[_i]), (PG8_LAS unsigned*)(lds + (bufoff) + ldsw + _i * 8192), 16, 0, 0); } while (0)
; #define PG8_LDA(dst, b, h) do { _Pragma("unroll") for (int m = 0; m < 4; ++m) _Pragma("unroll") for (int k = 0; k < 2; ++k) dst[m][k] = *(const PG8_LAS bf16x8*)(lds + PG8_SA(b, h) + aoff + m * 2048 + k * 1024); } while (0)
; #define PG8_LDB(dst, b, h) do { _Pragma("unroll") for (int n = 0; n < 2; ++n) _Pragma("unroll") for (int k = 0; k < 2; ++k) dst[n][k] = *(const PG8_LAS bf16x8*)(lds + PG8_SB(b, h) + boff + n * 2048 + k * 1024); } while (0)
; #define PG8_MMA(ai, bj, At, Bt) do { __builtin_amdgcn_s_setprio(1); _Pragma("unroll") for (int m = 0; m < 4; ++m) _Pragma("unroll") for (int n = 0; n < 2; ++n) _Pragma("unroll") for (int k = 0; k < 2; ++k) \
;         acc[ai][bj][m][n] = __builtin_amdgcn_mfma_f32_16x16x32_bf16(Bt[n][k], At[m][k], acc[ai][bj][m][n], 0, 0, 0); __builtin_amdgcn_s_setprio(0); } while (0)
; #define PG8_WAIT_V(n) asm volatile("s_waitcnt vmcnt(" #n ")" ::: "memory")
; #define PG8_WAIT_L(n) asm volatile("s_waitcnt lgkmcnt(" #n ")" ::: "memory")
; #define PG8_BAR __builtin_amdgcn_s_barrier()
; #define PG8_SCHED __builtin_amdgcn_sched_barrier(0)
; #define PG8_STAGE(bufoff, gbase, voff) do { _Pragma("unroll") for (int _i = 0; _i < 2; ++_i) \
;         __builtin_amdgcn_global_load_lds((const unsigned*)((const char*)(gbase) + (voff)[_i]), (PG8_LAS unsigned*)(lds + (bufoff) + ldsw + _i * 8192), 16, 0, 0); } while (0)
; #define PG8_WAIT_V(n) asm volatile("s_waitcnt vmcnt(" #n ")" ::: "memory")
; template <class Epi, class Sched, bool ALIGN_EPI = false>
; __device__ __forceinline__ void gemm_phase(PG8_LAS unsigned char* lds, const Gemm g, const Sched& S, const Epi& E) {
;     ...
;             PG8_LDB(B0, 0, 0); PG8_LDB(B1, 0, 1); PG8_SCHED; PG8_LDA(At, 0, 0); PG8_STAGE(PG8_SA(1, 1), a1 + hstepA, voffA);
;             PG8_WAIT_V(8); PG8_WAIT_L(0); PG8_BAR; PG8_MMA(0, 0, At, B0); PG8_MMA(0, 1, At, B1); PG8_BAR; PG8_SCHED;
;             PG8_LDA(At, 0, 1); PG8_STAGE(PG8_SB(0, 0), b2, voffB); PG8_STAGE(PG8_SB(0, 1), b2 + hstepB, voffB); PG8_STAGE(PG8_SA(0, 0), a2, voffA);
;             PG8_WAIT_V(8); PG8_WAIT_L(0); PG8_BAR; PG8_MMA(1, 0, At, B0); PG8_MMA(1, 1, At, B1); PG8_BAR; PG8_SCHED;
.LBB0_734:
	ds_read_b128 v[130:133], v165
	ds_read_b128 v[134:137], v165 offset:1024
	ds_read_b128 v[158:161], v165 offset:2048
	ds_read_b128 v[170:173], v165 offset:3072
	ds_read_b128 v[174:177], v166
	ds_read_b128 v[178:181], v166 offset:1024
	ds_read_b128 v[182:185], v166 offset:2048
	ds_read_b128 v[186:189], v166 offset:3072
	s_add_u32 s34, s52, 0xfff80080
	s_addc_u32 s35, s53, -1
	s_cmp_eq_u32 s85, 28
	s_cselect_b32 s55, s13, s35
	s_cselect_b32 s54, s27, s34
	s_cselect_b32 s35, s25, s84
	s_cselect_b32 s34, s82, s83
	v_lshl_add_u64 v[162:163], s[52:53], 0, v[150:151]
	s_add_i32 m0, s61, 0xc000
	ds_read_b128 v[190:193], v167
	ds_read_b128 v[194:197], v167 offset:1024
	ds_read_b128 v[198:201], v167 offset:2048
	ds_read_b128 v[202:205], v167 offset:3072
	ds_read_b128 v[206:209], v167 offset:4096
	ds_read_b128 v[210:213], v167 offset:5120
	ds_read_b128 v[214:217], v167 offset:6144
	ds_read_b128 v[218:221], v167 offset:7168
	global_load_lds_dwordx4 v[162:163], off
	v_lshl_add_u64 v[162:163], s[52:53], 0, v[152:153]
	s_add_i32 m0, s61, 0xe000
	s_nop 0
	global_load_lds_dwordx4 v[162:163], off
	s_waitcnt vmcnt(8)
	s_waitcnt lgkmcnt(0)
	s_barrier
	s_waitcnt lgkmcnt(0)
	v_mfma_f32_16x16x32_bf16 v[126:129], v[130:133], v[190:193], v[126:129]
	v_mfma_f32_16x16x32_bf16 v[122:125], v[158:161], v[190:193], v[122:125]
	v_mfma_f32_16x16x32_bf16 v[114:117], v[130:133], v[198:201], v[114:117]
	v_mfma_f32_16x16x32_bf16 v[106:109], v[158:161], v[198:201], v[106:109]
	v_mfma_f32_16x16x32_bf16 v[98:101], v[130:133], v[206:209], v[98:101]
	v_mfma_f32_16x16x32_bf16 v[90:93], v[158:161], v[206:209], v[90:93]
	v_mfma_f32_16x16x32_bf16 v[82:85], v[130:133], v[214:217], v[82:85]
	v_mfma_f32_16x16x32_bf16 v[74:77], v[158:161], v[214:217], v[74:77]
	v_mfma_f32_16x16x32_bf16 v[126:129], v[134:137], v[194:197], v[126:129]
	v_mfma_f32_16x16x32_bf16 v[122:125], v[170:173], v[194:197], v[122:125]
	v_mfma_f32_16x16x32_bf16 v[114:117], v[134:137], v[202:205], v[114:117]
	v_mfma_f32_16x16x32_bf16 v[106:109], v[170:173], v[202:205], v[106:109]
	v_mfma_f32_16x16x32_bf16 v[98:101], v[134:137], v[210:213], v[98:101]
	v_mfma_f32_16x16x32_bf16 v[90:93], v[170:173], v[210:213], v[90:93]
	v_mfma_f32_16x16x32_bf16 v[82:85], v[134:137], v[218:221], v[82:85]
	v_mfma_f32_16x16x32_bf16 v[74:77], v[170:173], v[218:221], v[74:77]
	v_mfma_f32_16x16x32_bf16 v[118:121], v[174:177], v[190:193], v[118:121]
	v_mfma_f32_16x16x32_bf16 v[110:113], v[182:185], v[190:193], v[110:113]
	v_mfma_f32_16x16x32_bf16 v[102:105], v[174:177], v[198:201], v[102:105]
	v_mfma_f32_16x16x32_bf16 v[94:97], v[182:185], v[198:201], v[94:97]
	v_mfma_f32_16x16x32_bf16 v[86:89], v[174:177], v[206:209], v[86:89]
	v_mfma_f32_16x16x32_bf16 v[78:81], v[182:185], v[206:209], v[78:81]
	v_mfma_f32_16x16x32_bf16 v[70:73], v[174:177], v[214:217], v[70:73]
	v_mfma_f32_16x16x32_bf16 v[66:69], v[182:185], v[214:217], v[66:69]
	v_mfma_f32_16x16x32_bf16 v[118:121], v[178:181], v[194:197], v[118:121]
	v_mfma_f32_16x16x32_bf16 v[110:113], v[186:189], v[194:197], v[110:113]
	v_mfma_f32_16x16x32_bf16 v[102:105], v[178:181], v[202:205], v[102:105]
	v_mfma_f32_16x16x32_bf16 v[94:97], v[186:189], v[202:205], v[94:97]
	v_mfma_f32_16x16x32_bf16 v[86:89], v[178:181], v[210:213], v[86:89]
	v_mfma_f32_16x16x32_bf16 v[78:81], v[186:189], v[210:213], v[78:81]
	v_mfma_f32_16x16x32_bf16 v[70:73], v[178:181], v[218:221], v[70:73]
	v_mfma_f32_16x16x32_bf16 v[66:69], v[186:189], v[218:221], v[66:69]
	s_barrier
	s_add_i32 s88, s72, s58
	v_lshl_add_u64 v[162:163], s[34:35], 0, v[140:141]
	s_mov_b32 m0, s88
	ds_read_b128 v[190:193], v167 offset:16384
	ds_read_b128 v[194:197], v167 offset:17408
	ds_read_b128 v[198:201], v167 offset:18432
	ds_read_b128 v[202:205], v167 offset:19456
	ds_read_b128 v[206:209], v167 offset:20480
	ds_read_b128 v[210:213], v167 offset:21504
	ds_read_b128 v[214:217], v167 offset:22528
	ds_read_b128 v[218:221], v167 offset:23552
	global_load_lds_dwordx4 v[162:163], off
	s_add_i32 m0, s88, 0x2000
	s_add_u32 s88, s34, 0x80000
	v_lshl_add_u64 v[222:223], s[34:35], 0, v[144:145]
	s_addc_u32 s89, s35, 0
	s_add_i32 s90, s73, s58
	global_load_lds_dwordx4 v[222:223], off
	v_lshl_add_u64 v[224:225], s[88:89], 0, v[140:141]
	s_mov_b32 m0, s90
	v_lshl_add_u64 v[226:227], s[54:55], 0, v[142:143]
	global_load_lds_dwordx4 v[224:225], off
	v_lshl_add_u64 v[224:225], s[88:89], 0, v[144:145]
	s_add_i32 m0, s90, 0x2000
	s_nop 0
	global_load_lds_dwordx4 v[224:225], off
	v_lshl_add_u64 v[224:225], s[54:55], 0, v[138:139]
	s_mov_b32 m0, s61
	s_nop 0
	global_load_lds_dwordx4 v[224:225], off
	s_mov_b32 m0, s62
	s_nop 0
	global_load_lds_dwordx4 v[226:227], off
	s_waitcnt vmcnt(8)
	s_waitcnt lgkmcnt(0)
	s_barrier
; #define PG8_STAGE(bufoff, gbase, voff) do { _Pragma("unroll") for (int _i = 0; _i < 2; ++_i) \
;         __builtin_amdgcn_global_load_lds((const unsigned*)((const char*)(gbase) + (voff)[_i]), (PG8_LAS unsigned*)(lds + (bufoff) + ldsw + _i * 8192), 16, 0, 0); } while (0)
; #define PG8_LDA(dst, b, h) do { _Pragma("unroll") for (int m = 0; m < 4; ++m) _Pragma("unroll") for (int k = 0; k < 2; ++k) dst[m][k] = *(const PG8_LAS bf16x8*)(lds + PG8_SA(b, h) + aoff + m * 2048 + k * 1024); } while (0)
; #define PG8_LDB(dst, b, h) do { _Pragma("unroll") for (int n = 0; n < 2; ++n) _Pragma("unroll") for (int k = 0; k < 2; ++k) dst[n][k] = *(const PG8_LAS bf16x8*)(lds + PG8_SB(b, h) + boff + n * 2048 + k * 1024); } while (0)
; #define PG8_MMA(ai, bj, At, Bt) do { __builtin_amdgcn_s_setprio(1); _Pragma("unroll") for (int m = 0; m < 4; ++m) _Pragma("unroll") for (int n = 0; n < 2; ++n) _Pragma("unroll") for (int k = 0; k < 2; ++k) \
;         acc[ai][bj][m][n] = __builtin_amdgcn_mfma_f32_16x16x32_bf16(Bt[n][k], At[m][k], acc[ai][bj][m][n], 0, 0, 0); __builtin_amdgcn_s_setprio(0); } while (0)
; #define PG8_WAIT_V(n) asm volatile("s_waitcnt vmcnt(" #n ")" ::: "memory")
; #define PG8_WAIT_L(n) asm volatile("s_waitcnt lgkmcnt(" #n ")" ::: "memory")
; #define PG8_BAR __builtin_amdgcn_s_barrier()
; #define PG8_SCHED __builtin_amdgcn_sched_barrier(0)
; #define PG8_STAGE(bufoff, gbase, voff) do { _Pragma("unroll") for (int _i = 0; _i < 2; ++_i) \
;         __builtin_amdgcn_global_load_lds((const unsigned*)((const char*)(gbase) + (voff)[_i]), (PG8_LAS unsigned*)(lds + (bufoff) + ldsw + _i * 8192), 16, 0, 0); } while (0)
; #define PG8_WAIT_V(n) asm volatile("s_waitcnt vmcnt(" #n ")" ::: "memory")
; #define PG8_WAIT_L(n) asm volatile("s_waitcnt lgkmcnt(" #n ")" ::: "memory")
; #define PG8_BAR __builtin_amdgcn_s_barrier()
; template <class Epi, class Sched, bool ALIGN_EPI = false>
; __device__ __forceinline__ void gemm_phase(PG8_LAS unsigned char* lds, const Gemm g, const Sched& S, const Epi& E) {
;     ...
;             PG8_WAIT_V(8); PG8_WAIT_L(0); PG8_BAR; PG8_MMA(1, 0, At, B0); PG8_MMA(1, 1, At, B1); PG8_BAR; PG8_SCHED;
;             PG8_LDB(B0, 1, 0); PG8_LDB(B1, 1, 1); PG8_SCHED; PG8_LDA(At, 1, 0); PG8_STAGE(PG8_SA(0, 1), a2 + hstepA, voffA);
;             PG8_WAIT_V(8); PG8_WAIT_L(0); PG8_BAR; PG8_MMA(0, 0, At, B0); PG8_MMA(0, 1, At, B1); PG8_BAR; PG8_SCHED;
	s_waitcnt lgkmcnt(0)
	v_mfma_f32_16x16x32_bf16 v[62:65], v[130:133], v[190:193], v[62:65]
	v_mfma_f32_16x16x32_bf16 v[58:61], v[158:161], v[190:193], v[58:61]
	v_mfma_f32_16x16x32_bf16 v[54:57], v[130:133], v[198:201], v[54:57]
	v_mfma_f32_16x16x32_bf16 v[46:49], v[158:161], v[198:201], v[46:49]
	v_mfma_f32_16x16x32_bf16 v[38:41], v[130:133], v[206:209], v[38:41]
	v_mfma_f32_16x16x32_bf16 v[30:33], v[158:161], v[206:209], v[30:33]
	v_mfma_f32_16x16x32_bf16 v[22:25], v[130:133], v[214:217], v[22:25]
	v_mfma_f32_16x16x32_bf16 v[14:17], v[158:161], v[214:217], v[14:17]
	v_mfma_f32_16x16x32_bf16 v[62:65], v[134:137], v[194:197], v[62:65]
	v_mfma_f32_16x16x32_bf16 v[58:61], v[170:173], v[194:197], v[58:61]
	v_mfma_f32_16x16x32_bf16 v[54:57], v[134:137], v[202:205], v[54:57]
	v_mfma_f32_16x16x32_bf16 v[46:49], v[170:173], v[202:205], v[46:49]
	v_mfma_f32_16x16x32_bf16 v[38:41], v[134:137], v[210:213], v[38:41]
	v_mfma_f32_16x16x32_bf16 v[30:33], v[170:173], v[210:213], v[30:33]
	v_mfma_f32_16x16x32_bf16 v[22:25], v[134:137], v[218:221], v[22:25]
	v_mfma_f32_16x16x32_bf16 v[14:17], v[170:173], v[218:221], v[14:17]
	v_mfma_f32_16x16x32_bf16 v[50:53], v[174:177], v[190:193], v[50:53]
	v_mfma_f32_16x16x32_bf16 v[42:45], v[182:185], v[190:193], v[42:45]
	v_mfma_f32_16x16x32_bf16 v[34:37], v[174:177], v[198:201], v[34:37]
	v_mfma_f32_16x16x32_bf16 v[26:29], v[182:185], v[198:201], v[26:29]
	v_mfma_f32_16x16x32_bf16 v[18:21], v[174:177], v[206:209], v[18:21]
	v_mfma_f32_16x16x32_bf16 v[10:13], v[182:185], v[206:209], v[10:13]
	v_mfma_f32_16x16x32_bf16 v[6:9], v[174:177], v[214:217], v[6:9]
	v_mfma_f32_16x16x32_bf16 v[2:5], v[182:185], v[214:217], v[2:5]
	v_mfma_f32_16x16x32_bf16 v[50:53], v[178:181], v[194:197], v[50:53]
	v_mfma_f32_16x16x32_bf16 v[42:45], v[186:189], v[194:197], v[42:45]
	v_mfma_f32_16x16x32_bf16 v[34:37], v[178:181], v[202:205], v[34:37]
	v_mfma_f32_16x16x32_bf16 v[26:29], v[186:189], v[202:205], v[26:29]
	v_mfma_f32_16x16x32_bf16 v[18:21], v[178:181], v[210:213], v[18:21]
	v_mfma_f32_16x16x32_bf16 v[10:13], v[186:189], v[210:213], v[10:13]
	v_mfma_f32_16x16x32_bf16 v[6:9], v[178:181], v[218:221], v[6:9]
	v_mfma_f32_16x16x32_bf16 v[2:5], v[186:189], v[218:221], v[2:5]
	s_barrier
	s_add_i32 s88, 0, 0x18000
	v_add_u32_e32 v146, s88, v164
	s_add_i32 s89, 0, 0x1c000
	ds_read_b128 v[130:133], v146
	ds_read_b128 v[134:137], v146 offset:1024
	ds_read_b128 v[158:161], v146 offset:2048
	ds_read_b128 v[170:173], v146 offset:3072
	v_add_u32_e32 v146, s89, v164
	ds_read_b128 v[174:177], v146
	ds_read_b128 v[178:181], v146 offset:1024
	ds_read_b128 v[182:185], v146 offset:2048
	ds_read_b128 v[186:189], v146 offset:3072
	s_add_u32 s54, s54, 0x80000
	s_addc_u32 s55, s55, 0
	s_mov_b32 m0, s63
	v_lshl_add_u64 v[228:229], s[54:55], 0, v[138:139]
	ds_read_b128 v[190:193], v167 offset:32768
	ds_read_b128 v[194:197], v167 offset:33792
	ds_read_b128 v[198:201], v167 offset:34816
	ds_read_b128 v[202:205], v167 offset:35840
	ds_read_b128 v[206:209], v167 offset:36864
	ds_read_b128 v[210:213], v167 offset:37888
	ds_read_b128 v[214:217], v167 offset:38912
	ds_read_b128 v[218:221], v167 offset:39936
	global_load_lds_dwordx4 v[228:229], off
	v_lshl_add_u64 v[228:229], s[54:55], 0, v[142:143]
	s_mov_b32 m0, s64
	s_nop 0
	global_load_lds_dwordx4 v[228:229], off
	s_waitcnt vmcnt(8)
	s_waitcnt lgkmcnt(0)
	s_barrier
	s_waitcnt lgkmcnt(0)
	v_mfma_f32_16x16x32_bf16 v[126:129], v[130:133], v[190:193], v[126:129]
	v_mfma_f32_16x16x32_bf16 v[122:125], v[158:161], v[190:193], v[122:125]
	v_mfma_f32_16x16x32_bf16 v[114:117], v[130:133], v[198:201], v[114:117]
	v_mfma_f32_16x16x32_bf16 v[106:109], v[158:161], v[198:201], v[106:109]
	v_mfma_f32_16x16x32_bf16 v[98:101], v[130:133], v[206:209], v[98:101]
	v_mfma_f32_16x16x32_bf16 v[90:93], v[158:161], v[206:209], v[90:93]
	v_mfma_f32_16x16x32_bf16 v[82:85], v[130:133], v[214:217], v[82:85]
	v_mfma_f32_16x16x32_bf16 v[74:77], v[158:161], v[214:217], v[74:77]
	v_mfma_f32_16x16x32_bf16 v[126:129], v[134:137], v[194:197], v[126:129]
	v_mfma_f32_16x16x32_bf16 v[122:125], v[170:173], v[194:197], v[122:125]
	v_mfma_f32_16x16x32_bf16 v[114:117], v[134:137], v[202:205], v[114:117]
	v_mfma_f32_16x16x32_bf16 v[106:109], v[170:173], v[202:205], v[106:109]
	v_mfma_f32_16x16x32_bf16 v[98:101], v[134:137], v[210:213], v[98:101]
	v_mfma_f32_16x16x32_bf16 v[90:93], v[170:173], v[210:213], v[90:93]
	v_mfma_f32_16x16x32_bf16 v[82:85], v[134:137], v[218:221], v[82:85]
	v_mfma_f32_16x16x32_bf16 v[74:77], v[170:173], v[218:221], v[74:77]
	v_mfma_f32_16x16x32_bf16 v[118:121], v[174:177], v[190:193], v[118:121]
	v_mfma_f32_16x16x32_bf16 v[110:113], v[182:185], v[190:193], v[110:113]
	v_mfma_f32_16x16x32_bf16 v[102:105], v[174:177], v[198:201], v[102:105]
	v_mfma_f32_16x16x32_bf16 v[94:97], v[182:185], v[198:201], v[94:97]
	v_mfma_f32_16x16x32_bf16 v[86:89], v[174:177], v[206:209], v[86:89]
	v_mfma_f32_16x16x32_bf16 v[78:81], v[182:185], v[206:209], v[78:81]
	v_mfma_f32_16x16x32_bf16 v[70:73], v[174:177], v[214:217], v[70:73]
	v_mfma_f32_16x16x32_bf16 v[66:69], v[182:185], v[214:217], v[66:69]
	v_mfma_f32_16x16x32_bf16 v[118:121], v[178:181], v[194:197], v[118:121]
	v_mfma_f32_16x16x32_bf16 v[110:113], v[186:189], v[194:197], v[110:113]
	v_mfma_f32_16x16x32_bf16 v[102:105], v[178:181], v[202:205], v[102:105]
	v_mfma_f32_16x16x32_bf16 v[94:97], v[186:189], v[202:205], v[94:97]
	v_mfma_f32_16x16x32_bf16 v[86:89], v[178:181], v[210:213], v[86:89]
	v_mfma_f32_16x16x32_bf16 v[78:81], v[186:189], v[210:213], v[78:81]
	v_mfma_f32_16x16x32_bf16 v[70:73], v[178:181], v[218:221], v[70:73]
	v_mfma_f32_16x16x32_bf16 v[66:69], v[186:189], v[218:221], v[66:69]
	s_barrier
; #define PG8_STAGE(bufoff, gbase, voff) do { _Pragma("unroll") for (int _i = 0; _i < 2; ++_i) \
;         __builtin_amdgcn_global_load_lds((const unsigned*)((const char*)(gbase) + (voff)[_i]), (PG8_LAS unsigned*)(lds + (bufoff) + ldsw + _i * 8192), 16, 0, 0); } while (0)
; #define PG8_LDA(dst, b, h) do { _Pragma("unroll") for (int m = 0; m < 4; ++m) _Pragma("unroll") for (int k = 0; k < 2; ++k) dst[m][k] = *(const PG8_LAS bf16x8*)(lds + PG8_SA(b, h) + aoff + m * 2048 + k * 1024); } while (0)
; #define PG8_MMA(ai, bj, At, Bt) do { __builtin_amdgcn_s_setprio(1); _Pragma("unroll") for (int m = 0; m < 4; ++m) _Pragma("unroll") for (int n = 0; n < 2; ++n) _Pragma("unroll") for (int k = 0; k < 2; ++k) \
;         acc[ai][bj][m][n] = __builtin_amdgcn_mfma_f32_16x16x32_bf16(Bt[n][k], At[m][k], acc[ai][bj][m][n], 0, 0, 0); __builtin_amdgcn_s_setprio(0); } while (0)
; #define PG8_WAIT_V(n) asm volatile("s_waitcnt vmcnt(" #n ")" ::: "memory")
; #define PG8_WAIT_L(n) asm volatile("s_waitcnt lgkmcnt(" #n ")" ::: "memory")
; #define PG8_BAR __builtin_amdgcn_s_barrier()
; #define PG8_SCHED __builtin_amdgcn_sched_barrier(0)
; #define PG8_STAGE(bufoff, gbase, voff) do { _Pragma("unroll") for (int _i = 0; _i < 2; ++_i) \
;         __builtin_amdgcn_global_load_lds((const unsigned*)((const char*)(gbase) + (voff)[_i]), (PG8_LAS unsigned*)(lds + (bufoff) + ldsw + _i * 8192), 16, 0, 0); } while (0)
; #define PG8_LDA(dst, b, h) do { _Pragma("unroll") for (int m = 0; m < 4; ++m) dst[m] = cat8(*(const PG8_LAS bf16x8*)(lds + PG8_SA(b, h) + aoff + m * 2048), *(const PG8_LAS bf16x8*)(lds + PG8_SA(b, h) + (aoff ^ 16) + m * 2048)); } while (0)
; #define PG8_WAIT_V(n) asm volatile("s_waitcnt vmcnt(" #n ")" ::: "memory")
; #define PG8_WAIT_L(n) asm volatile("s_waitcnt lgkmcnt(" #n ")" ::: "memory")
; #define PG8_BAR __builtin_amdgcn_s_barrier()
; #define PG8_SCHED __builtin_amdgcn_sched_barrier(0)
; template <class Epi, class Sched, bool ALIGN_EPI = false>
; __device__ __forceinline__ void gemm_phase(PG8_LAS unsigned char* lds, const Gemm g, const Sched& S, const Epi& E) {
;     ...
;             PG8_LDA(At, 1, 1); PG8_STAGE(PG8_SB(1, 0), b3, voffB); PG8_STAGE(PG8_SB(1, 1), b3 + hstepB, voffB); PG8_STAGE(PG8_SA(1, 0), a3, voffA);
;             PG8_WAIT_V(8); PG8_WAIT_L(0); PG8_BAR; PG8_MMA(1, 0, At, B0); PG8_MMA(1, 1, At, B1); PG8_BAR; PG8_SCHED;
;         }
	s_add_i32 s54, s88, s58
	v_lshl_add_u64 v[162:163], v[162:163], 0, s[10:11]
	s_mov_b32 m0, s54
	ds_read_b128 v[190:193], v167 offset:49152
	ds_read_b128 v[194:197], v167 offset:50176
	ds_read_b128 v[198:201], v167 offset:51200
	ds_read_b128 v[202:205], v167 offset:52224
	ds_read_b128 v[206:209], v167 offset:53248
	ds_read_b128 v[210:213], v167 offset:54272
	ds_read_b128 v[214:217], v167 offset:55296
	ds_read_b128 v[218:221], v167 offset:56320
	global_load_lds_dwordx4 v[162:163], off
	s_add_i32 m0, s54, 0x2000
	s_add_u32 s34, s34, 0x80080
	v_lshl_add_u64 v[162:163], v[222:223], 0, s[10:11]
	s_addc_u32 s35, s35, 0
	s_add_i32 s54, s89, s58
	global_load_lds_dwordx4 v[162:163], off
	v_lshl_add_u64 v[162:163], s[34:35], 0, v[140:141]
	s_mov_b32 m0, s54
	s_nop 0
	global_load_lds_dwordx4 v[162:163], off
	v_lshl_add_u64 v[162:163], s[34:35], 0, v[144:145]
	s_add_i32 m0, s54, 0x2000
	s_nop 0
	global_load_lds_dwordx4 v[162:163], off
	v_lshl_add_u64 v[162:163], v[224:225], 0, s[10:11]
	s_mov_b32 m0, s70
	s_nop 0
	global_load_lds_dwordx4 v[162:163], off
	v_lshl_add_u64 v[162:163], v[226:227], 0, s[10:11]
	s_mov_b32 m0, s71
	s_nop 0
	global_load_lds_dwordx4 v[162:163], off
	s_waitcnt vmcnt(8)
	s_waitcnt lgkmcnt(0)
	s_barrier
	s_waitcnt lgkmcnt(0)
	v_mfma_f32_16x16x32_bf16 v[62:65], v[130:133], v[190:193], v[62:65]
	v_mfma_f32_16x16x32_bf16 v[58:61], v[158:161], v[190:193], v[58:61]
	v_mfma_f32_16x16x32_bf16 v[54:57], v[130:133], v[198:201], v[54:57]
	v_mfma_f32_16x16x32_bf16 v[46:49], v[158:161], v[198:201], v[46:49]
	v_mfma_f32_16x16x32_bf16 v[38:41], v[130:133], v[206:209], v[38:41]
	v_mfma_f32_16x16x32_bf16 v[30:33], v[158:161], v[206:209], v[30:33]
	v_mfma_f32_16x16x32_bf16 v[22:25], v[130:133], v[214:217], v[22:25]
	v_mfma_f32_16x16x32_bf16 v[14:17], v[158:161], v[214:217], v[14:17]
	v_mfma_f32_16x16x32_bf16 v[62:65], v[134:137], v[194:197], v[62:65]
	v_mfma_f32_16x16x32_bf16 v[58:61], v[170:173], v[194:197], v[58:61]
	v_mfma_f32_16x16x32_bf16 v[54:57], v[134:137], v[202:205], v[54:57]
	v_mfma_f32_16x16x32_bf16 v[46:49], v[170:173], v[202:205], v[46:49]
	v_mfma_f32_16x16x32_bf16 v[38:41], v[134:137], v[210:213], v[38:41]
	v_mfma_f32_16x16x32_bf16 v[30:33], v[170:173], v[210:213], v[30:33]
	v_mfma_f32_16x16x32_bf16 v[22:25], v[134:137], v[218:221], v[22:25]
	v_mfma_f32_16x16x32_bf16 v[14:17], v[170:173], v[218:221], v[14:17]
	v_mfma_f32_16x16x32_bf16 v[50:53], v[174:177], v[190:193], v[50:53]
	v_mfma_f32_16x16x32_bf16 v[42:45], v[182:185], v[190:193], v[42:45]
	v_mfma_f32_16x16x32_bf16 v[34:37], v[174:177], v[198:201], v[34:37]
	v_mfma_f32_16x16x32_bf16 v[26:29], v[182:185], v[198:201], v[26:29]
	v_mfma_f32_16x16x32_bf16 v[18:21], v[174:177], v[206:209], v[18:21]
	v_mfma_f32_16x16x32_bf16 v[10:13], v[182:185], v[206:209], v[10:13]
	v_mfma_f32_16x16x32_bf16 v[6:9], v[174:177], v[214:217], v[6:9]
	v_mfma_f32_16x16x32_bf16 v[2:5], v[182:185], v[214:217], v[2:5]
	v_mfma_f32_16x16x32_bf16 v[50:53], v[178:181], v[194:197], v[50:53]
	v_mfma_f32_16x16x32_bf16 v[42:45], v[186:189], v[194:197], v[42:45]
	v_mfma_f32_16x16x32_bf16 v[34:37], v[178:181], v[202:205], v[34:37]
	v_mfma_f32_16x16x32_bf16 v[26:29], v[186:189], v[202:205], v[26:29]
	v_mfma_f32_16x16x32_bf16 v[18:21], v[178:181], v[210:213], v[18:21]
	v_mfma_f32_16x16x32_bf16 v[10:13], v[186:189], v[210:213], v[10:13]
	v_mfma_f32_16x16x32_bf16 v[6:9], v[178:181], v[218:221], v[6:9]
	v_mfma_f32_16x16x32_bf16 v[2:5], v[186:189], v[218:221], v[2:5]
	s_barrier
	s_add_i32 s85, s85, 2
	s_add_u32 s52, s52, 0x100
	s_addc_u32 s53, s53, 0
	s_add_u32 s83, s83, 0x100
	s_addc_u32 s84, s84, 0
	s_cmp_gt_u32 s85, 29
	s_cbranch_scc0 .LBB0_734
	s_and_b64 vcc, exec, s[14:15]
	s_cbranch_vccz .LBB0_737
	s_barrier

; #define PG8_STAGE(bufoff, gbase, voff) do { _Pragma("unroll") for (int _i = 0; _i < 2; ++_i) \
;         __builtin_amdgcn_global_load_lds((const unsigned*)((const char*)(gbase) + (voff)[_i]), (PG8_LAS unsigned*)(lds + (bufoff) + ldsw + _i * 8192), 16, 0, 0); } while (0)
; #define PG8_LDA(dst, b, h) do { _Pragma("unroll") for (int m = 0; m < 4; ++m) _Pragma("unroll") for (int k = 0; k < 2; ++k) dst[m][k] = *(const PG8_LAS bf16x8*)(lds + PG8_SA(b, h) + aoff + m * 2048 + k * 1024); } while (0)
; #define PG8_LDB(dst, b, h) do { _Pragma("unroll") for (int n = 0; n < 2; ++n) _Pragma("unroll") for (int k = 0; k < 2; ++k) dst[n][k] = *(const PG8_LAS bf16x8*)(lds + PG8_SB(b, h) + boff + n * 2048 + k * 1024); } while (0)
; #define PG8_MMA(ai, bj, At, Bt) do { __builtin_amdgcn_s_setprio(1); _Pragma("unroll") for (int m = 0; m < 4; ++m) _Pragma("unroll") for (int n = 0; n < 2; ++n) _Pragma("unroll") for (int k = 0; k < 2; ++k) \
;         acc[ai][bj][m][n] = __builtin_amdgcn_mfma_f32_16x16x32_bf16(Bt[n][k], At[m][k], acc[ai][bj][m][n], 0, 0, 0); __builtin_amdgcn_s_setprio(0); } while (0)
; #define PG8_WAIT_V(n) asm volatile("s_waitcnt vmcnt(" #n ")" ::: "memory")
; #define PG8_WAIT_L(n) asm volatile("s_waitcnt lgkmcnt(" #n ")" ::: "memory")
; #define PG8_BAR __builtin_amdgcn_s_barrier()
; template <class Epi, class Sched, bool ALIGN_EPI = false>
; __device__ __forceinline__ void gemm_phase8(PG8_LAS unsigned char* lds, const Gemm g, const Sched& S, const Epi& E) {
;     ...
;             const bool last = (t == nt - 2);
;             const char* a1 = cA + (size_t)(t + 1) * kstep;
;             const char* a2 = last ? nA : cA + (size_t)(t + 2) * kstep; const char* b2 = last ? nB : cB + (size_t)(t + 2) * kstep;
;             const char* a3 = a2 + kstep; const char* b3 = b2 + kstep;
;             if (last && has_next) S.a_ready(nxt);
;             PG8_LDB(B0, 0, 0); PG8_LDB(B1, 0, 1); PG8_SCHED; PG8_LDA(At, 0, 0); PG8_STAGE(PG8_SA(1, 1), a1 + hstepA, voffA);
;             PG8_WAIT_V(8); PG8_WAIT_L(0); PG8_BAR; PG8_MMA(0, 0, At, B0); PG8_MMA(0, 1, At, B1); PG8_BAR; PG8_SCHED;
;             PG8_LDA(At, 0, 1); PG8_STAGE(PG8_SB(0, 0), b2, voffB); PG8_STAGE(PG8_SB(0, 1), b2 + hstepB, voffB); PG8_STAGE(PG8_SA(0, 0), a2, voffA);
;             PG8_WAIT_V(8); PG8_WAIT_L(0); PG8_BAR; PG8_MMA(1, 0, At, B0); PG8_MMA(1, 1, At, B1); PG8_BAR; PG8_SCHED;
.LBB0_1187:
	ds_read_b128 v[18:21], v187
	ds_read_b128 v[26:29], v187 offset:2048
	ds_read_b128 v[22:25], v188
	ds_read_b128 v[30:33], v188 offset:2048
	ds_read_b128 v[2:5], v189
	ds_read_b128 v[10:13], v189 offset:2048
	ds_read_b128 v[6:9], v190
	ds_read_b128 v[14:17], v190 offset:2048
	s_add_i32 s80, s58, 2
	s_add_u32 s34, s56, 0xfffc0080
	s_addc_u32 s35, s57, -1
	s_cmp_eq_u32 s77, s58
	s_cselect_b32 s58, s31, s34
	s_cselect_b32 s59, s19, s35
	s_cselect_b32 s35, s21, s79
	s_cselect_b32 s34, s75, s78
	v_lshl_add_u64 v[218:219], s[56:57], 0, v[170:171]
	s_add_i32 m0, s29, 0xc000
	ds_read_b128 v[174:177], v191
	ds_read_b128 v[194:197], v191 offset:2048
	ds_read_b128 v[178:181], v192
	ds_read_b128 v[198:201], v192 offset:2048
	ds_read_b128 v[202:205], v191 offset:4096
	ds_read_b128 v[210:213], v191 offset:6144
	ds_read_b128 v[206:209], v192 offset:4096
	ds_read_b128 v[214:217], v192 offset:6144
	global_load_lds_dwordx4 v[218:219], off
	v_lshl_add_u64 v[218:219], s[56:57], 0, v[172:173]
	s_add_i32 m0, s29, 0xe000
	s_nop 0
	global_load_lds_dwordx4 v[218:219], off
	s_waitcnt vmcnt(8)
	s_waitcnt lgkmcnt(0)
	s_barrier
	s_waitcnt lgkmcnt(0)
	v_mfma_scale_f32_16x16x128_f8f6f4 v[158:161], v[18:25], v[174:181], v[158:161], v1, v182 op_sel_hi:[0,0,0]
	v_mfma_scale_f32_16x16x128_f8f6f4 v[154:157], v[26:33], v[174:181], v[154:157], v1, v182 op_sel_hi:[0,0,0]
	v_mfma_scale_f32_16x16x128_f8f6f4 v[150:153], v[18:25], v[194:201], v[150:153], v1, v182 op_sel_hi:[0,0,0]
	v_mfma_scale_f32_16x16x128_f8f6f4 v[138:141], v[26:33], v[194:201], v[138:141], v1, v182 op_sel_hi:[0,0,0]
	v_mfma_scale_f32_16x16x128_f8f6f4 v[130:133], v[18:25], v[202:209], v[130:133], v1, v182 op_sel_hi:[0,0,0]
	v_mfma_scale_f32_16x16x128_f8f6f4 v[122:125], v[26:33], v[202:209], v[122:125], v1, v182 op_sel_hi:[0,0,0]
	v_mfma_scale_f32_16x16x128_f8f6f4 v[118:121], v[18:25], v[210:217], v[118:121], v1, v182 op_sel_hi:[0,0,0]
	v_mfma_scale_f32_16x16x128_f8f6f4 v[106:109], v[26:33], v[210:217], v[106:109], v1, v182 op_sel_hi:[0,0,0]
	v_mfma_scale_f32_16x16x128_f8f6f4 v[146:149], v[2:9], v[174:181], v[146:149], v1, v182 op_sel_hi:[0,0,0]
	v_mfma_scale_f32_16x16x128_f8f6f4 v[142:145], v[10:17], v[174:181], v[142:145], v1, v182 op_sel_hi:[0,0,0]
	v_mfma_scale_f32_16x16x128_f8f6f4 v[134:137], v[2:9], v[194:201], v[134:137], v1, v182 op_sel_hi:[0,0,0]
	v_mfma_scale_f32_16x16x128_f8f6f4 v[126:129], v[10:17], v[194:201], v[126:129], v1, v182 op_sel_hi:[0,0,0]
	v_mfma_scale_f32_16x16x128_f8f6f4 v[114:117], v[2:9], v[202:209], v[114:117], v1, v182 op_sel_hi:[0,0,0]
	v_mfma_scale_f32_16x16x128_f8f6f4 v[110:113], v[10:17], v[202:209], v[110:113], v1, v182 op_sel_hi:[0,0,0]
	v_mfma_scale_f32_16x16x128_f8f6f4 v[102:105], v[2:9], v[210:217], v[102:105], v1, v182 op_sel_hi:[0,0,0]
	v_mfma_scale_f32_16x16x128_f8f6f4 v[98:101], v[10:17], v[210:217], v[98:101], v1, v182 op_sel_hi:[0,0,0]
	s_barrier
	s_add_i32 s81, s71, s61
	v_lshl_add_u64 v[174:175], s[34:35], 0, v[164:165]
	s_mov_b32 m0, s81
	ds_read_b128 v[194:197], v191 offset:16384
	ds_read_b128 v[202:205], v191 offset:18432
	ds_read_b128 v[198:201], v192 offset:16384
	ds_read_b128 v[206:209], v192 offset:18432
	ds_read_b128 v[210:213], v191 offset:20480
	ds_read_b128 v[218:221], v191 offset:22528
	ds_read_b128 v[214:217], v192 offset:20480
	ds_read_b128 v[222:225], v192 offset:22528
	global_load_lds_dwordx4 v[174:175], off
	s_add_i32 m0, s81, 0x2000
	s_add_u32 s82, s34, 0x40000
	v_lshl_add_u64 v[176:177], s[34:35], 0, v[168:169]
	s_addc_u32 s83, s35, 0
	s_add_i32 s81, s72, s61
	global_load_lds_dwordx4 v[176:177], off
	v_lshl_add_u64 v[178:179], s[82:83], 0, v[164:165]
	s_mov_b32 m0, s81
	v_lshl_add_u64 v[180:181], s[58:59], 0, v[166:167]
	global_load_lds_dwordx4 v[178:179], off
	v_lshl_add_u64 v[178:179], s[82:83], 0, v[168:169]
	s_add_i32 m0, s81, 0x2000
	s_nop 0
	global_load_lds_dwordx4 v[178:179], off
	v_lshl_add_u64 v[178:179], s[58:59], 0, v[162:163]
	s_mov_b32 m0, s29
	s_nop 0
	global_load_lds_dwordx4 v[178:179], off
	s_mov_b32 m0, s53
	s_nop 0
	global_load_lds_dwordx4 v[180:181], off
	s_waitcnt vmcnt(8)
	s_waitcnt lgkmcnt(0)
	s_barrier
	s_waitcnt lgkmcnt(0)
	v_mfma_scale_f32_16x16x128_f8f6f4 v[94:97], v[18:25], v[194:201], v[94:97], v1, v182 op_sel_hi:[0,0,0]
	v_mfma_scale_f32_16x16x128_f8f6f4 v[90:93], v[26:33], v[194:201], v[90:93], v1, v182 op_sel_hi:[0,0,0]
	v_mfma_scale_f32_16x16x128_f8f6f4 v[82:85], v[18:25], v[202:209], v[82:85], v1, v182 op_sel_hi:[0,0,0]
	v_mfma_scale_f32_16x16x128_f8f6f4 v[74:77], v[26:33], v[202:209], v[74:77], v1, v182 op_sel_hi:[0,0,0]
	v_mfma_scale_f32_16x16x128_f8f6f4 v[66:69], v[18:25], v[210:217], v[66:69], v1, v182 op_sel_hi:[0,0,0]
	v_mfma_scale_f32_16x16x128_f8f6f4 v[58:61], v[26:33], v[210:217], v[58:61], v1, v182 op_sel_hi:[0,0,0]
	v_mfma_scale_f32_16x16x128_f8f6f4 v[50:53], v[18:25], v[218:225], v[50:53], v1, v182 op_sel_hi:[0,0,0]
	v_mfma_scale_f32_16x16x128_f8f6f4 v[42:45], v[26:33], v[218:225], v[42:45], v1, v182 op_sel_hi:[0,0,0]
	v_mfma_scale_f32_16x16x128_f8f6f4 v[86:89], v[2:9], v[194:201], v[86:89], v1, v182 op_sel_hi:[0,0,0]
	v_mfma_scale_f32_16x16x128_f8f6f4 v[78:81], v[10:17], v[194:201], v[78:81], v1, v182 op_sel_hi:[0,0,0]
	v_mfma_scale_f32_16x16x128_f8f6f4 v[70:73], v[2:9], v[202:209], v[70:73], v1, v182 op_sel_hi:[0,0,0]
	v_mfma_scale_f32_16x16x128_f8f6f4 v[62:65], v[10:17], v[202:209], v[62:65], v1, v182 op_sel_hi:[0,0,0]
	v_mfma_scale_f32_16x16x128_f8f6f4 v[54:57], v[2:9], v[210:217], v[54:57], v1, v182 op_sel_hi:[0,0,0]
	v_mfma_scale_f32_16x16x128_f8f6f4 v[46:49], v[10:17], v[210:217], v[46:49], v1, v182 op_sel_hi:[0,0,0]
	v_mfma_scale_f32_16x16x128_f8f6f4 v[38:41], v[2:9], v[218:225], v[38:41], v1, v182 op_sel_hi:[0,0,0]
	v_mfma_scale_f32_16x16x128_f8f6f4 v[34:37], v[10:17], v[218:225], v[34:37], v1, v182 op_sel_hi:[0,0,0]
	s_barrier
; #define PG8_STAGE(bufoff, gbase, voff) do { _Pragma("unroll") for (int _i = 0; _i < 2; ++_i) \
;         __builtin_amdgcn_global_load_lds((const unsigned*)((const char*)(gbase) + (voff)[_i]), (PG8_LAS unsigned*)(lds + (bufoff) + ldsw + _i * 8192), 16, 0, 0); } while (0)
; #define PG8_LDA(dst, b, h) do { _Pragma("unroll") for (int m = 0; m < 4; ++m) _Pragma("unroll") for (int k = 0; k < 2; ++k) dst[m][k] = *(const PG8_LAS bf16x8*)(lds + PG8_SA(b, h) + aoff + m * 2048 + k * 1024); } while (0)
; #define PG8_LDB(dst, b, h) do { _Pragma("unroll") for (int n = 0; n < 2; ++n) _Pragma("unroll") for (int k = 0; k < 2; ++k) dst[n][k] = *(const PG8_LAS bf16x8*)(lds + PG8_SB(b, h) + boff + n * 2048 + k * 1024); } while (0)
; #define PG8_MMA(ai, bj, At, Bt) do { __builtin_amdgcn_s_setprio(1); _Pragma("unroll") for (int m = 0; m < 4; ++m) _Pragma("unroll") for (int n = 0; n < 2; ++n) _Pragma("unroll") for (int k = 0; k < 2; ++k) \
;         acc[ai][bj][m][n] = __builtin_amdgcn_mfma_f32_16x16x32_bf16(Bt[n][k], At[m][k], acc[ai][bj][m][n], 0, 0, 0); __builtin_amdgcn_s_setprio(0); } while (0)
; #define PG8_WAIT_V(n) asm volatile("s_waitcnt vmcnt(" #n ")" ::: "memory")
; #define PG8_WAIT_L(n) asm volatile("s_waitcnt lgkmcnt(" #n ")" ::: "memory")
; #define PG8_BAR __builtin_amdgcn_s_barrier()
; #define PG8_SCHED __builtin_amdgcn_sched_barrier(0)
; #define PG8_STAGE(bufoff, gbase, voff) do { _Pragma("unroll") for (int _i = 0; _i < 2; ++_i) \
;         __builtin_amdgcn_global_load_lds((const unsigned*)((const char*)(gbase) + (voff)[_i]), (PG8_LAS unsigned*)(lds + (bufoff) + ldsw + _i * 8192), 16, 0, 0); } while (0)
; #define PG8_BAR __builtin_amdgcn_s_barrier()
; template <class Epi, class Sched, bool ALIGN_EPI = false>
; __device__ __forceinline__ void gemm_phase8(PG8_LAS unsigned char* lds, const Gemm g, const Sched& S, const Epi& E) {
;     ...
;             PG8_LDB(B0, 1, 0); PG8_LDB(B1, 1, 1); PG8_SCHED; PG8_LDA(At, 1, 0); PG8_STAGE(PG8_SA(0, 1), a2 + hstepA, voffA);
;             PG8_WAIT_V(8); PG8_WAIT_L(0); PG8_BAR; PG8_MMA(0, 0, At, B0); PG8_MMA(0, 1, At, B1); PG8_BAR; PG8_SCHED;
;             PG8_LDA(At, 1, 1); PG8_STAGE(PG8_SB(1, 0), b3, voffB); PG8_STAGE(PG8_SB(1, 1), b3 + hstepB, voffB); PG8_STAGE(PG8_SA(1, 0), a3, voffA);
;             PG8_WAIT_V(8); PG8_WAIT_L(0); PG8_BAR; PG8_MMA(1, 0, At, B0); PG8_MMA(1, 1, At, B1); PG8_BAR; PG8_SCHED;
;         }
	s_add_i32 s81, 0, 0x18000
	s_add_i32 s82, 0, 0x1c000
	v_add_u32_e32 v6, s81, v184
	v_add_u32_e32 v14, s81, v185
	v_add_u32_e32 v22, s82, v184
	v_add_u32_e32 v30, s82, v185
	ds_read_b128 v[2:5], v6
	ds_read_b128 v[10:13], v6 offset:2048
	ds_read_b128 v[6:9], v14
	ds_read_b128 v[14:17], v14 offset:2048
	ds_read_b128 v[18:21], v22
	ds_read_b128 v[26:29], v22 offset:2048
	ds_read_b128 v[22:25], v30
	ds_read_b128 v[30:33], v30 offset:2048
	s_add_u32 s58, s58, 0x40000
	s_addc_u32 s59, s59, 0
	s_mov_b32 m0, s62
	v_lshl_add_u64 v[226:227], s[58:59], 0, v[162:163]
	ds_read_b128 v[194:197], v191 offset:32768
	ds_read_b128 v[202:205], v191 offset:34816
	ds_read_b128 v[198:201], v192 offset:32768
	ds_read_b128 v[206:209], v192 offset:34816
	ds_read_b128 v[210:213], v191 offset:36864
	ds_read_b128 v[218:221], v191 offset:38912
	ds_read_b128 v[214:217], v192 offset:36864
	ds_read_b128 v[222:225], v192 offset:38912
	global_load_lds_dwordx4 v[226:227], off
	v_lshl_add_u64 v[226:227], s[58:59], 0, v[166:167]
	s_mov_b32 m0, s63
	s_nop 0
	global_load_lds_dwordx4 v[226:227], off
	s_waitcnt vmcnt(8)
	s_waitcnt lgkmcnt(0)
	s_barrier
	s_waitcnt lgkmcnt(0)
	v_mfma_scale_f32_16x16x128_f8f6f4 v[158:161], v[2:9], v[194:201], v[158:161], v1, v182 op_sel_hi:[0,0,0]
	v_mfma_scale_f32_16x16x128_f8f6f4 v[154:157], v[10:17], v[194:201], v[154:157], v1, v182 op_sel_hi:[0,0,0]
	v_mfma_scale_f32_16x16x128_f8f6f4 v[150:153], v[2:9], v[202:209], v[150:153], v1, v182 op_sel_hi:[0,0,0]
	v_mfma_scale_f32_16x16x128_f8f6f4 v[138:141], v[10:17], v[202:209], v[138:141], v1, v182 op_sel_hi:[0,0,0]
	v_mfma_scale_f32_16x16x128_f8f6f4 v[130:133], v[2:9], v[210:217], v[130:133], v1, v182 op_sel_hi:[0,0,0]
	v_mfma_scale_f32_16x16x128_f8f6f4 v[122:125], v[10:17], v[210:217], v[122:125], v1, v182 op_sel_hi:[0,0,0]
	v_mfma_scale_f32_16x16x128_f8f6f4 v[118:121], v[2:9], v[218:225], v[118:121], v1, v182 op_sel_hi:[0,0,0]
	v_mfma_scale_f32_16x16x128_f8f6f4 v[106:109], v[10:17], v[218:225], v[106:109], v1, v182 op_sel_hi:[0,0,0]
	v_mfma_scale_f32_16x16x128_f8f6f4 v[146:149], v[18:25], v[194:201], v[146:149], v1, v182 op_sel_hi:[0,0,0]
	v_mfma_scale_f32_16x16x128_f8f6f4 v[142:145], v[26:33], v[194:201], v[142:145], v1, v182 op_sel_hi:[0,0,0]
	v_mfma_scale_f32_16x16x128_f8f6f4 v[134:137], v[18:25], v[202:209], v[134:137], v1, v182 op_sel_hi:[0,0,0]
	v_mfma_scale_f32_16x16x128_f8f6f4 v[126:129], v[26:33], v[202:209], v[126:129], v1, v182 op_sel_hi:[0,0,0]
	v_mfma_scale_f32_16x16x128_f8f6f4 v[114:117], v[18:25], v[210:217], v[114:117], v1, v182 op_sel_hi:[0,0,0]
	v_mfma_scale_f32_16x16x128_f8f6f4 v[110:113], v[26:33], v[210:217], v[110:113], v1, v182 op_sel_hi:[0,0,0]
	v_mfma_scale_f32_16x16x128_f8f6f4 v[102:105], v[18:25], v[218:225], v[102:105], v1, v182 op_sel_hi:[0,0,0]
	v_mfma_scale_f32_16x16x128_f8f6f4 v[98:101], v[26:33], v[218:225], v[98:101], v1, v182 op_sel_hi:[0,0,0]
	s_barrier
	s_add_i32 s58, s81, s61
	v_lshl_add_u64 v[174:175], v[174:175], 0, s[10:11]
	s_mov_b32 m0, s58
	ds_read_b128 v[194:197], v191 offset:49152
	ds_read_b128 v[202:205], v191 offset:51200
	ds_read_b128 v[198:201], v192 offset:49152
	ds_read_b128 v[206:209], v192 offset:51200
	ds_read_b128 v[210:213], v191 offset:53248
	ds_read_b128 v[218:221], v191 offset:55296
	ds_read_b128 v[214:217], v192 offset:53248
	ds_read_b128 v[222:225], v192 offset:55296
	global_load_lds_dwordx4 v[174:175], off
	s_add_i32 m0, s58, 0x2000
	s_add_u32 s34, s34, 0x40080
	v_lshl_add_u64 v[174:175], v[176:177], 0, s[10:11]
	s_addc_u32 s35, s35, 0
	s_add_i32 s58, s82, s61
	global_load_lds_dwordx4 v[174:175], off
	v_lshl_add_u64 v[174:175], s[34:35], 0, v[164:165]
	s_mov_b32 m0, s58
	s_nop 0
	global_load_lds_dwordx4 v[174:175], off
	v_lshl_add_u64 v[174:175], s[34:35], 0, v[168:169]
	s_add_i32 m0, s58, 0x2000
	s_nop 0
	global_load_lds_dwordx4 v[174:175], off
	v_lshl_add_u64 v[174:175], v[178:179], 0, s[10:11]
	s_mov_b32 m0, s69
	s_nop 0
	global_load_lds_dwordx4 v[174:175], off
	v_lshl_add_u64 v[174:175], v[180:181], 0, s[10:11]
	s_mov_b32 m0, s70
	s_nop 0
	global_load_lds_dwordx4 v[174:175], off
	s_waitcnt vmcnt(8)
	s_waitcnt lgkmcnt(0)
	s_barrier
	s_waitcnt lgkmcnt(0)
	v_mfma_scale_f32_16x16x128_f8f6f4 v[94:97], v[2:9], v[194:201], v[94:97], v1, v182 op_sel_hi:[0,0,0]
	v_mfma_scale_f32_16x16x128_f8f6f4 v[90:93], v[10:17], v[194:201], v[90:93], v1, v182 op_sel_hi:[0,0,0]
	v_mfma_scale_f32_16x16x128_f8f6f4 v[82:85], v[2:9], v[202:209], v[82:85], v1, v182 op_sel_hi:[0,0,0]
	v_mfma_scale_f32_16x16x128_f8f6f4 v[74:77], v[10:17], v[202:209], v[74:77], v1, v182 op_sel_hi:[0,0,0]
	v_mfma_scale_f32_16x16x128_f8f6f4 v[66:69], v[2:9], v[210:217], v[66:69], v1, v182 op_sel_hi:[0,0,0]
	v_mfma_scale_f32_16x16x128_f8f6f4 v[58:61], v[10:17], v[210:217], v[58:61], v1, v182 op_sel_hi:[0,0,0]
	v_mfma_scale_f32_16x16x128_f8f6f4 v[50:53], v[2:9], v[218:225], v[50:53], v1, v182 op_sel_hi:[0,0,0]
	v_mfma_scale_f32_16x16x128_f8f6f4 v[42:45], v[10:17], v[218:225], v[42:45], v1, v182 op_sel_hi:[0,0,0]
	v_mfma_scale_f32_16x16x128_f8f6f4 v[86:89], v[18:25], v[194:201], v[86:89], v1, v182 op_sel_hi:[0,0,0]
	v_mfma_scale_f32_16x16x128_f8f6f4 v[78:81], v[26:33], v[194:201], v[78:81], v1, v182 op_sel_hi:[0,0,0]
	v_mfma_scale_f32_16x16x128_f8f6f4 v[70:73], v[18:25], v[202:209], v[70:73], v1, v182 op_sel_hi:[0,0,0]
	v_mfma_scale_f32_16x16x128_f8f6f4 v[62:65], v[26:33], v[202:209], v[62:65], v1, v182 op_sel_hi:[0,0,0]
	v_mfma_scale_f32_16x16x128_f8f6f4 v[54:57], v[18:25], v[210:217], v[54:57], v1, v182 op_sel_hi:[0,0,0]
	v_mfma_scale_f32_16x16x128_f8f6f4 v[46:49], v[26:33], v[210:217], v[46:49], v1, v182 op_sel_hi:[0,0,0]
	v_mfma_scale_f32_16x16x128_f8f6f4 v[38:41], v[18:25], v[218:225], v[38:41], v1, v182 op_sel_hi:[0,0,0]
	v_mfma_scale_f32_16x16x128_f8f6f4 v[34:37], v[26:33], v[218:225], v[34:37], v1, v182 op_sel_hi:[0,0,0]
	s_barrier
	s_add_u32 s56, s56, 0x100
	s_addc_u32 s57, s57, 0
	s_add_u32 s78, s78, 0x100
	s_addc_u32 s79, s79, 0
	s_cmp_ge_u32 s80, s76
	s_mov_b32 s58, s80
	s_cbranch_scc0 .LBB0_1187
	s_and_b64 vcc, exec, s[12:13]
	s_cbranch_vccz .LBB0_1190
	s_barrier

; #define PG8_STAGE(bufoff, gbase, voff) do { _Pragma("unroll") for (int _i = 0; _i < 2; ++_i) \
;         __builtin_amdgcn_global_load_lds((const unsigned*)((const char*)(gbase) + (voff)[_i]), (PG8_LAS unsigned*)(lds + (bufoff) + ldsw + _i * 8192), 16, 0, 0); } while (0)
; #define PG8_LDA(dst, b, h) do { _Pragma("unroll") for (int m = 0; m < 4; ++m) _Pragma("unroll") for (int k = 0; k < 2; ++k) dst[m][k] = *(const PG8_LAS bf16x8*)(lds + PG8_SA(b, h) + aoff + m * 2048 + k * 1024); } while (0)
; #define PG8_LDB(dst, b, h) do { _Pragma("unroll") for (int n = 0; n < 2; ++n) _Pragma("unroll") for (int k = 0; k < 2; ++k) dst[n][k] = *(const PG8_LAS bf16x8*)(lds + PG8_SB(b, h) + boff + n * 2048 + k * 1024); } while (0)
; #define PG8_MMA(ai, bj, At, Bt) do { __builtin_amdgcn_s_setprio(1); _Pragma("unroll") for (int m = 0; m < 4; ++m) _Pragma("unroll") for (int n = 0; n < 2; ++n) _Pragma("unroll") for (int k = 0; k < 2; ++k) \
;         acc[ai][bj][m][n] = __builtin_amdgcn_mfma_f32_16x16x32_bf16(Bt[n][k], At[m][k], acc[ai][bj][m][n], 0, 0, 0); __builtin_amdgcn_s_setprio(0); } while (0)
; #define PG8_WAIT_V(n) asm volatile("s_waitcnt vmcnt(" #n ")" ::: "memory")
; #define PG8_WAIT_L(n) asm volatile("s_waitcnt lgkmcnt(" #n ")" ::: "memory")
; #define PG8_BAR __builtin_amdgcn_s_barrier()
; template <class Epi, class Sched, bool ALIGN_EPI = false>
; __device__ __forceinline__ void gemm_phase8(PG8_LAS unsigned char* lds, const Gemm g, const Sched& S, const Epi& E) {
;     ...
;             const bool last = (t == nt - 2);
;             const char* a1 = cA + (size_t)(t + 1) * kstep;
;             const char* a2 = last ? nA : cA + (size_t)(t + 2) * kstep; const char* b2 = last ? nB : cB + (size_t)(t + 2) * kstep;
;             const char* a3 = a2 + kstep; const char* b3 = b2 + kstep;
;             if (last && has_next) S.a_ready(nxt);
;             PG8_LDB(B0, 0, 0); PG8_LDB(B1, 0, 1); PG8_SCHED; PG8_LDA(At, 0, 0); PG8_STAGE(PG8_SA(1, 1), a1 + hstepA, voffA);
;             PG8_WAIT_V(8); PG8_WAIT_L(0); PG8_BAR; PG8_MMA(0, 0, At, B0); PG8_MMA(0, 1, At, B1); PG8_BAR; PG8_SCHED;
;             PG8_LDA(At, 0, 1); PG8_STAGE(PG8_SB(0, 0), b2, voffB); PG8_STAGE(PG8_SB(0, 1), b2 + hstepB, voffB); PG8_STAGE(PG8_SA(0, 0), a2, voffA);
;             PG8_WAIT_V(8); PG8_WAIT_L(0); PG8_BAR; PG8_MMA(1, 0, At, B0); PG8_MMA(1, 1, At, B1); PG8_BAR; PG8_SCHED;
.LBB0_1422:
	ds_read_b128 v[18:21], v191
	ds_read_b128 v[26:29], v191 offset:2048
	ds_read_b128 v[22:25], v192
	ds_read_b128 v[30:33], v192 offset:2048
	ds_read_b128 v[2:5], v193
	ds_read_b128 v[10:13], v193 offset:2048
	ds_read_b128 v[6:9], v194
	ds_read_b128 v[14:17], v194 offset:2048
	s_add_u32 s22, s20, 0xfffc0080
	s_addc_u32 s23, s21, -1
	s_cmp_eq_u32 s55, 12
	s_cselect_b32 s25, s13, s23
	s_cselect_b32 s24, s45, s22
	s_cselect_b32 s23, s11, s54
	s_cselect_b32 s22, s52, s53
	v_lshl_add_u64 v[222:223], s[20:21], 0, v[170:171]
	s_add_i32 m0, s19, 0xc000
	ds_read_b128 v[178:181], v195
	ds_read_b128 v[198:201], v195 offset:2048
	ds_read_b128 v[182:185], v196
	ds_read_b128 v[202:205], v196 offset:2048
	ds_read_b128 v[206:209], v195 offset:4096
	ds_read_b128 v[214:217], v195 offset:6144
	ds_read_b128 v[210:213], v196 offset:4096
	ds_read_b128 v[218:221], v196 offset:6144
	global_load_lds_dwordx4 v[222:223], off
	v_lshl_add_u64 v[222:223], s[20:21], 0, v[172:173]
	s_add_i32 m0, s19, 0xe000
	s_nop 0
	global_load_lds_dwordx4 v[222:223], off
	s_waitcnt vmcnt(8)
	s_waitcnt lgkmcnt(0)
	s_barrier
	s_waitcnt lgkmcnt(0)
	v_mfma_scale_f32_16x16x128_f8f6f4 v[158:161], v[18:25], v[178:185], v[158:161], v1, v186 op_sel_hi:[0,0,0]
	v_mfma_scale_f32_16x16x128_f8f6f4 v[150:153], v[26:33], v[178:185], v[150:153], v1, v186 op_sel_hi:[0,0,0]
	v_mfma_scale_f32_16x16x128_f8f6f4 v[142:145], v[18:25], v[198:205], v[142:145], v1, v186 op_sel_hi:[0,0,0]
	v_mfma_scale_f32_16x16x128_f8f6f4 v[134:137], v[26:33], v[198:205], v[134:137], v1, v186 op_sel_hi:[0,0,0]
	v_mfma_scale_f32_16x16x128_f8f6f4 v[126:129], v[18:25], v[206:213], v[126:129], v1, v186 op_sel_hi:[0,0,0]
	v_mfma_scale_f32_16x16x128_f8f6f4 v[118:121], v[26:33], v[206:213], v[118:121], v1, v186 op_sel_hi:[0,0,0]
	v_mfma_scale_f32_16x16x128_f8f6f4 v[110:113], v[18:25], v[214:221], v[110:113], v1, v186 op_sel_hi:[0,0,0]
	v_mfma_scale_f32_16x16x128_f8f6f4 v[102:105], v[26:33], v[214:221], v[102:105], v1, v186 op_sel_hi:[0,0,0]
	v_mfma_scale_f32_16x16x128_f8f6f4 v[154:157], v[2:9], v[178:185], v[154:157], v1, v186 op_sel_hi:[0,0,0]
	v_mfma_scale_f32_16x16x128_f8f6f4 v[146:149], v[10:17], v[178:185], v[146:149], v1, v186 op_sel_hi:[0,0,0]
	v_mfma_scale_f32_16x16x128_f8f6f4 v[138:141], v[2:9], v[198:205], v[138:141], v1, v186 op_sel_hi:[0,0,0]
	v_mfma_scale_f32_16x16x128_f8f6f4 v[130:133], v[10:17], v[198:205], v[130:133], v1, v186 op_sel_hi:[0,0,0]
	v_mfma_scale_f32_16x16x128_f8f6f4 v[122:125], v[2:9], v[206:213], v[122:125], v1, v186 op_sel_hi:[0,0,0]
	v_mfma_scale_f32_16x16x128_f8f6f4 v[114:117], v[10:17], v[206:213], v[114:117], v1, v186 op_sel_hi:[0,0,0]
	v_mfma_scale_f32_16x16x128_f8f6f4 v[106:109], v[2:9], v[214:221], v[106:109], v1, v186 op_sel_hi:[0,0,0]
	v_mfma_scale_f32_16x16x128_f8f6f4 v[98:101], v[10:17], v[214:221], v[98:101], v1, v186 op_sel_hi:[0,0,0]
	s_barrier
	s_add_i32 s56, s41, s30
	v_lshl_add_u64 v[178:179], s[22:23], 0, v[164:165]
	s_mov_b32 m0, s56
	ds_read_b128 v[198:201], v195 offset:16384
	ds_read_b128 v[206:209], v195 offset:18432
	ds_read_b128 v[202:205], v196 offset:16384
	ds_read_b128 v[210:213], v196 offset:18432
	ds_read_b128 v[214:217], v195 offset:20480
	ds_read_b128 v[222:225], v195 offset:22528
	ds_read_b128 v[218:221], v196 offset:20480
	ds_read_b128 v[226:229], v196 offset:22528
	global_load_lds_dwordx4 v[178:179], off
	s_add_i32 m0, s56, 0x2000
	s_add_u32 s56, s22, 0x40000
	v_lshl_add_u64 v[180:181], s[22:23], 0, v[168:169]
	s_addc_u32 s57, s23, 0
	s_add_i32 s58, s42, s30
	global_load_lds_dwordx4 v[180:181], off
	v_lshl_add_u64 v[182:183], s[56:57], 0, v[164:165]
	s_mov_b32 m0, s58
	v_lshl_add_u64 v[184:185], s[24:25], 0, v[166:167]
	global_load_lds_dwordx4 v[182:183], off
	v_lshl_add_u64 v[182:183], s[56:57], 0, v[168:169]
	s_add_i32 m0, s58, 0x2000
	s_nop 0
	global_load_lds_dwordx4 v[182:183], off
	v_lshl_add_u64 v[182:183], s[24:25], 0, v[162:163]
	s_mov_b32 m0, s19
	s_nop 0
	global_load_lds_dwordx4 v[182:183], off
	s_mov_b32 m0, s34
	s_nop 0
	global_load_lds_dwordx4 v[184:185], off
	s_waitcnt vmcnt(8)
	s_waitcnt lgkmcnt(0)
	s_barrier
	s_waitcnt lgkmcnt(0)
	v_mfma_scale_f32_16x16x128_f8f6f4 v[94:97], v[18:25], v[198:205], v[94:97], v1, v186 op_sel_hi:[0,0,0]
	v_mfma_scale_f32_16x16x128_f8f6f4 v[86:89], v[26:33], v[198:205], v[86:89], v1, v186 op_sel_hi:[0,0,0]
	v_mfma_scale_f32_16x16x128_f8f6f4 v[78:81], v[18:25], v[206:213], v[78:81], v1, v186 op_sel_hi:[0,0,0]
	v_mfma_scale_f32_16x16x128_f8f6f4 v[70:73], v[26:33], v[206:213], v[70:73], v1, v186 op_sel_hi:[0,0,0]
	v_mfma_scale_f32_16x16x128_f8f6f4 v[62:65], v[18:25], v[214:221], v[62:65], v1, v186 op_sel_hi:[0,0,0]
	v_mfma_scale_f32_16x16x128_f8f6f4 v[54:57], v[26:33], v[214:221], v[54:57], v1, v186 op_sel_hi:[0,0,0]
	v_mfma_scale_f32_16x16x128_f8f6f4 v[46:49], v[18:25], v[222:229], v[46:49], v1, v186 op_sel_hi:[0,0,0]
	v_mfma_scale_f32_16x16x128_f8f6f4 v[38:41], v[26:33], v[222:229], v[38:41], v1, v186 op_sel_hi:[0,0,0]
	v_mfma_scale_f32_16x16x128_f8f6f4 v[90:93], v[2:9], v[198:205], v[90:93], v1, v186 op_sel_hi:[0,0,0]
	v_mfma_scale_f32_16x16x128_f8f6f4 v[82:85], v[10:17], v[198:205], v[82:85], v1, v186 op_sel_hi:[0,0,0]
	v_mfma_scale_f32_16x16x128_f8f6f4 v[74:77], v[2:9], v[206:213], v[74:77], v1, v186 op_sel_hi:[0,0,0]
	v_mfma_scale_f32_16x16x128_f8f6f4 v[66:69], v[10:17], v[206:213], v[66:69], v1, v186 op_sel_hi:[0,0,0]
	v_mfma_scale_f32_16x16x128_f8f6f4 v[58:61], v[2:9], v[214:221], v[58:61], v1, v186 op_sel_hi:[0,0,0]
	v_mfma_scale_f32_16x16x128_f8f6f4 v[50:53], v[10:17], v[214:221], v[50:53], v1, v186 op_sel_hi:[0,0,0]
	v_mfma_scale_f32_16x16x128_f8f6f4 v[42:45], v[2:9], v[222:229], v[42:45], v1, v186 op_sel_hi:[0,0,0]
	v_mfma_scale_f32_16x16x128_f8f6f4 v[34:37], v[10:17], v[222:229], v[34:37], v1, v186 op_sel_hi:[0,0,0]
	s_barrier
; #define PG8_STAGE(bufoff, gbase, voff) do { _Pragma("unroll") for (int _i = 0; _i < 2; ++_i) \
;         __builtin_amdgcn_global_load_lds((const unsigned*)((const char*)(gbase) + (voff)[_i]), (PG8_LAS unsigned*)(lds + (bufoff) + ldsw + _i * 8192), 16, 0, 0); } while (0)
; #define PG8_LDA(dst, b, h) do { _Pragma("unroll") for (int m = 0; m < 4; ++m) _Pragma("unroll") for (int k = 0; k < 2; ++k) dst[m][k] = *(const PG8_LAS bf16x8*)(lds + PG8_SA(b, h) + aoff + m * 2048 + k * 1024); } while (0)
; #define PG8_LDB(dst, b, h) do { _Pragma("unroll") for (int n = 0; n < 2; ++n) _Pragma("unroll") for (int k = 0; k < 2; ++k) dst[n][k] = *(const PG8_LAS bf16x8*)(lds + PG8_SB(b, h) + boff + n * 2048 + k * 1024); } while (0)
; #define PG8_MMA(ai, bj, At, Bt) do { __builtin_amdgcn_s_setprio(1); _Pragma("unroll") for (int m = 0; m < 4; ++m) _Pragma("unroll") for (int n = 0; n < 2; ++n) _Pragma("unroll") for (int k = 0; k < 2; ++k) \
;         acc[ai][bj][m][n] = __builtin_amdgcn_mfma_f32_16x16x32_bf16(Bt[n][k], At[m][k], acc[ai][bj][m][n], 0, 0, 0); __builtin_amdgcn_s_setprio(0); } while (0)
; #define PG8_WAIT_V(n) asm volatile("s_waitcnt vmcnt(" #n ")" ::: "memory")
; #define PG8_WAIT_L(n) asm volatile("s_waitcnt lgkmcnt(" #n ")" ::: "memory")
; #define PG8_BAR __builtin_amdgcn_s_barrier()
; #define PG8_SCHED __builtin_amdgcn_sched_barrier(0)
; #define PG8_STAGE(bufoff, gbase, voff) do { _Pragma("unroll") for (int _i = 0; _i < 2; ++_i) \
;         __builtin_amdgcn_global_load_lds((const unsigned*)((const char*)(gbase) + (voff)[_i]), (PG8_LAS unsigned*)(lds + (bufoff) + ldsw + _i * 8192), 16, 0, 0); } while (0)
; #define PG8_BAR __builtin_amdgcn_s_barrier()
; template <class Epi, class Sched, bool ALIGN_EPI = false>
; __device__ __forceinline__ void gemm_phase8(PG8_LAS unsigned char* lds, const Gemm g, const Sched& S, const Epi& E) {
;     ...
;             PG8_LDB(B0, 1, 0); PG8_LDB(B1, 1, 1); PG8_SCHED; PG8_LDA(At, 1, 0); PG8_STAGE(PG8_SA(0, 1), a2 + hstepA, voffA);
;             PG8_WAIT_V(8); PG8_WAIT_L(0); PG8_BAR; PG8_MMA(0, 0, At, B0); PG8_MMA(0, 1, At, B1); PG8_BAR; PG8_SCHED;
;             PG8_LDA(At, 1, 1); PG8_STAGE(PG8_SB(1, 0), b3, voffB); PG8_STAGE(PG8_SB(1, 1), b3 + hstepB, voffB); PG8_STAGE(PG8_SA(1, 0), a3, voffA);
;             PG8_WAIT_V(8); PG8_WAIT_L(0); PG8_BAR; PG8_MMA(1, 0, At, B0); PG8_MMA(1, 1, At, B1); PG8_BAR; PG8_SCHED;
;         }
	s_add_i32 s56, 0, 0x18000
	s_add_i32 s57, 0, 0x1c000
	v_add_u32_e32 v6, s56, v187
	v_add_u32_e32 v14, s56, v188
	v_add_u32_e32 v22, s57, v187
	v_add_u32_e32 v30, s57, v188
	ds_read_b128 v[2:5], v6
	ds_read_b128 v[10:13], v6 offset:2048
	ds_read_b128 v[6:9], v14
	ds_read_b128 v[14:17], v14 offset:2048
	ds_read_b128 v[18:21], v22
	ds_read_b128 v[26:29], v22 offset:2048
	ds_read_b128 v[22:25], v30
	ds_read_b128 v[30:33], v30 offset:2048
	s_add_u32 s24, s24, 0x40000
	s_addc_u32 s25, s25, 0
	s_mov_b32 m0, s35
	v_lshl_add_u64 v[230:231], s[24:25], 0, v[162:163]
	ds_read_b128 v[198:201], v195 offset:32768
	ds_read_b128 v[206:209], v195 offset:34816
	ds_read_b128 v[202:205], v196 offset:32768
	ds_read_b128 v[210:213], v196 offset:34816
	ds_read_b128 v[214:217], v195 offset:36864
	ds_read_b128 v[222:225], v195 offset:38912
	ds_read_b128 v[218:221], v196 offset:36864
	ds_read_b128 v[226:229], v196 offset:38912
	global_load_lds_dwordx4 v[230:231], off
	v_lshl_add_u64 v[230:231], s[24:25], 0, v[166:167]
	s_mov_b32 m0, s36
	s_nop 0
	global_load_lds_dwordx4 v[230:231], off
	s_waitcnt vmcnt(8)
	s_waitcnt lgkmcnt(0)
	s_barrier
	s_waitcnt lgkmcnt(0)
	v_mfma_scale_f32_16x16x128_f8f6f4 v[158:161], v[2:9], v[198:205], v[158:161], v1, v186 op_sel_hi:[0,0,0]
	v_mfma_scale_f32_16x16x128_f8f6f4 v[150:153], v[10:17], v[198:205], v[150:153], v1, v186 op_sel_hi:[0,0,0]
	v_mfma_scale_f32_16x16x128_f8f6f4 v[142:145], v[2:9], v[206:213], v[142:145], v1, v186 op_sel_hi:[0,0,0]
	v_mfma_scale_f32_16x16x128_f8f6f4 v[134:137], v[10:17], v[206:213], v[134:137], v1, v186 op_sel_hi:[0,0,0]
	v_mfma_scale_f32_16x16x128_f8f6f4 v[126:129], v[2:9], v[214:221], v[126:129], v1, v186 op_sel_hi:[0,0,0]
	v_mfma_scale_f32_16x16x128_f8f6f4 v[118:121], v[10:17], v[214:221], v[118:121], v1, v186 op_sel_hi:[0,0,0]
	v_mfma_scale_f32_16x16x128_f8f6f4 v[110:113], v[2:9], v[222:229], v[110:113], v1, v186 op_sel_hi:[0,0,0]
	v_mfma_scale_f32_16x16x128_f8f6f4 v[102:105], v[10:17], v[222:229], v[102:105], v1, v186 op_sel_hi:[0,0,0]
	v_mfma_scale_f32_16x16x128_f8f6f4 v[154:157], v[18:25], v[198:205], v[154:157], v1, v186 op_sel_hi:[0,0,0]
	v_mfma_scale_f32_16x16x128_f8f6f4 v[146:149], v[26:33], v[198:205], v[146:149], v1, v186 op_sel_hi:[0,0,0]
	v_mfma_scale_f32_16x16x128_f8f6f4 v[138:141], v[18:25], v[206:213], v[138:141], v1, v186 op_sel_hi:[0,0,0]
	v_mfma_scale_f32_16x16x128_f8f6f4 v[130:133], v[26:33], v[206:213], v[130:133], v1, v186 op_sel_hi:[0,0,0]
	v_mfma_scale_f32_16x16x128_f8f6f4 v[122:125], v[18:25], v[214:221], v[122:125], v1, v186 op_sel_hi:[0,0,0]
	v_mfma_scale_f32_16x16x128_f8f6f4 v[114:117], v[26:33], v[214:221], v[114:117], v1, v186 op_sel_hi:[0,0,0]
	v_mfma_scale_f32_16x16x128_f8f6f4 v[106:109], v[18:25], v[222:229], v[106:109], v1, v186 op_sel_hi:[0,0,0]
	v_mfma_scale_f32_16x16x128_f8f6f4 v[98:101], v[26:33], v[222:229], v[98:101], v1, v186 op_sel_hi:[0,0,0]
	s_barrier
	s_add_i32 s24, s56, s30
	v_lshl_add_u64 v[178:179], v[178:179], 0, s[6:7]
	s_mov_b32 m0, s24
	ds_read_b128 v[198:201], v195 offset:49152
	ds_read_b128 v[206:209], v195 offset:51200
	ds_read_b128 v[202:205], v196 offset:49152
	ds_read_b128 v[210:213], v196 offset:51200
	ds_read_b128 v[214:217], v195 offset:53248
	ds_read_b128 v[222:225], v195 offset:55296
	ds_read_b128 v[218:221], v196 offset:53248
	ds_read_b128 v[226:229], v196 offset:55296
	global_load_lds_dwordx4 v[178:179], off
	s_add_i32 m0, s24, 0x2000
	s_add_u32 s22, s22, 0x40080
	v_lshl_add_u64 v[178:179], v[180:181], 0, s[6:7]
	s_addc_u32 s23, s23, 0
	s_add_i32 s24, s57, s30
	global_load_lds_dwordx4 v[178:179], off
	v_lshl_add_u64 v[178:179], s[22:23], 0, v[164:165]
	s_mov_b32 m0, s24
	s_nop 0
	global_load_lds_dwordx4 v[178:179], off
	v_lshl_add_u64 v[178:179], s[22:23], 0, v[168:169]
	s_add_i32 m0, s24, 0x2000
	s_nop 0
	global_load_lds_dwordx4 v[178:179], off
	v_lshl_add_u64 v[178:179], v[182:183], 0, s[6:7]
	s_mov_b32 m0, s39
	s_nop 0
	global_load_lds_dwordx4 v[178:179], off
	v_lshl_add_u64 v[178:179], v[184:185], 0, s[6:7]
	s_mov_b32 m0, s40
	s_nop 0
	global_load_lds_dwordx4 v[178:179], off
	s_waitcnt vmcnt(8)
	s_waitcnt lgkmcnt(0)
	s_barrier
	s_waitcnt lgkmcnt(0)
	v_mfma_scale_f32_16x16x128_f8f6f4 v[94:97], v[2:9], v[198:205], v[94:97], v1, v186 op_sel_hi:[0,0,0]
	v_mfma_scale_f32_16x16x128_f8f6f4 v[86:89], v[10:17], v[198:205], v[86:89], v1, v186 op_sel_hi:[0,0,0]
	v_mfma_scale_f32_16x16x128_f8f6f4 v[78:81], v[2:9], v[206:213], v[78:81], v1, v186 op_sel_hi:[0,0,0]
	v_mfma_scale_f32_16x16x128_f8f6f4 v[70:73], v[10:17], v[206:213], v[70:73], v1, v186 op_sel_hi:[0,0,0]
	v_mfma_scale_f32_16x16x128_f8f6f4 v[62:65], v[2:9], v[214:221], v[62:65], v1, v186 op_sel_hi:[0,0,0]
	v_mfma_scale_f32_16x16x128_f8f6f4 v[54:57], v[10:17], v[214:221], v[54:57], v1, v186 op_sel_hi:[0,0,0]
	v_mfma_scale_f32_16x16x128_f8f6f4 v[46:49], v[2:9], v[222:229], v[46:49], v1, v186 op_sel_hi:[0,0,0]
	v_mfma_scale_f32_16x16x128_f8f6f4 v[38:41], v[10:17], v[222:229], v[38:41], v1, v186 op_sel_hi:[0,0,0]
	v_mfma_scale_f32_16x16x128_f8f6f4 v[90:93], v[18:25], v[198:205], v[90:93], v1, v186 op_sel_hi:[0,0,0]
	v_mfma_scale_f32_16x16x128_f8f6f4 v[82:85], v[26:33], v[198:205], v[82:85], v1, v186 op_sel_hi:[0,0,0]
	v_mfma_scale_f32_16x16x128_f8f6f4 v[74:77], v[18:25], v[206:213], v[74:77], v1, v186 op_sel_hi:[0,0,0]
	v_mfma_scale_f32_16x16x128_f8f6f4 v[66:69], v[26:33], v[206:213], v[66:69], v1, v186 op_sel_hi:[0,0,0]
	v_mfma_scale_f32_16x16x128_f8f6f4 v[58:61], v[18:25], v[214:221], v[58:61], v1, v186 op_sel_hi:[0,0,0]
	v_mfma_scale_f32_16x16x128_f8f6f4 v[50:53], v[26:33], v[214:221], v[50:53], v1, v186 op_sel_hi:[0,0,0]
	v_mfma_scale_f32_16x16x128_f8f6f4 v[42:45], v[18:25], v[222:229], v[42:45], v1, v186 op_sel_hi:[0,0,0]
	v_mfma_scale_f32_16x16x128_f8f6f4 v[34:37], v[26:33], v[222:229], v[34:37], v1, v186 op_sel_hi:[0,0,0]
	s_barrier
	s_add_i32 s55, s55, 2
	s_add_u32 s20, s20, 0x100
	s_addc_u32 s21, s21, 0
	s_add_u32 s53, s53, 0x100
	s_addc_u32 s54, s54, 0
	s_cmp_gt_u32 s55, 13
	s_cbranch_scc0 .LBB0_1422
	s_and_b64 vcc, exec, s[8:9]
	s_cbranch_vccz .LBB0_1425
	s_barrier

; #define PG8_STAGE(bufoff, gbase, voff) do { _Pragma("unroll") for (int _i = 0; _i < 2; ++_i) \
;         __builtin_amdgcn_global_load_lds((const unsigned*)((const char*)(gbase) + (voff)[_i]), (PG8_LAS unsigned*)(lds + (bufoff) + ldsw + _i * 8192), 16, 0, 0); } while (0)
; #define PG8_LDA(dst, b, h) do { _Pragma("unroll") for (int m = 0; m < 4; ++m) _Pragma("unroll") for (int k = 0; k < 2; ++k) dst[m][k] = *(const PG8_LAS bf16x8*)(lds + PG8_SA(b, h) + aoff + m * 2048 + k * 1024); } while (0)
; #define PG8_LDB(dst, b, h) do { _Pragma("unroll") for (int n = 0; n < 2; ++n) _Pragma("unroll") for (int k = 0; k < 2; ++k) dst[n][k] = *(const PG8_LAS bf16x8*)(lds + PG8_SB(b, h) + boff + n * 2048 + k * 1024); } while (0)
; #define PG8_MMA(ai, bj, At, Bt) do { __builtin_amdgcn_s_setprio(1); _Pragma("unroll") for (int m = 0; m < 4; ++m) _Pragma("unroll") for (int n = 0; n < 2; ++n) _Pragma("unroll") for (int k = 0; k < 2; ++k) \
;         acc[ai][bj][m][n] = __builtin_amdgcn_mfma_f32_16x16x32_bf16(Bt[n][k], At[m][k], acc[ai][bj][m][n], 0, 0, 0); __builtin_amdgcn_s_setprio(0); } while (0)
; #define PG8_WAIT_V(n) asm volatile("s_waitcnt vmcnt(" #n ")" ::: "memory")
; #define PG8_WAIT_L(n) asm volatile("s_waitcnt lgkmcnt(" #n ")" ::: "memory")
; #define PG8_BAR __builtin_amdgcn_s_barrier()
; template <class Epi, class Sched, bool ALIGN_EPI = false>
; __device__ __forceinline__ void gemm_phase8(PG8_LAS unsigned char* lds, const Gemm g, const Sched& S, const Epi& E) {
;     ...
;             const bool last = (t == nt - 2);
;             const char* a1 = cA + (size_t)(t + 1) * kstep;
;             const char* a2 = last ? nA : cA + (size_t)(t + 2) * kstep; const char* b2 = last ? nB : cB + (size_t)(t + 2) * kstep;
;             const char* a3 = a2 + kstep; const char* b3 = b2 + kstep;
;             if (last && has_next) S.a_ready(nxt);
;             PG8_LDB(B0, 0, 0); PG8_LDB(B1, 0, 1); PG8_SCHED; PG8_LDA(At, 0, 0); PG8_STAGE(PG8_SA(1, 1), a1 + hstepA, voffA);
;             PG8_WAIT_V(8); PG8_WAIT_L(0); PG8_BAR; PG8_MMA(0, 0, At, B0); PG8_MMA(0, 1, At, B1); PG8_BAR; PG8_SCHED;
;             PG8_LDA(At, 0, 1); PG8_STAGE(PG8_SB(0, 0), b2, voffB); PG8_STAGE(PG8_SB(0, 1), b2 + hstepB, voffB); PG8_STAGE(PG8_SA(0, 0), a2, voffA);
;             PG8_WAIT_V(8); PG8_WAIT_L(0); PG8_BAR; PG8_MMA(1, 0, At, B0); PG8_MMA(1, 1, At, B1); PG8_BAR; PG8_SCHED;
.LBB0_1511:
	ds_read_b128 v[18:21], v187
	ds_read_b128 v[26:29], v187 offset:2048
	ds_read_b128 v[22:25], v188
	ds_read_b128 v[30:33], v188 offset:2048
	ds_read_b128 v[2:5], v189
	ds_read_b128 v[10:13], v189 offset:2048
	ds_read_b128 v[6:9], v190
	ds_read_b128 v[14:17], v190 offset:2048
	s_add_i32 s82, s40, 2
	s_add_u32 s34, s38, 0xfff50080
	s_addc_u32 s35, s39, -1
	s_cmp_eq_u32 s79, s40
	s_cselect_b32 s40, s26, s34
	s_cselect_b32 s41, s27, s35
	s_cselect_b32 s35, s29, s81
	s_cselect_b32 s34, s28, s80
	v_lshl_add_u64 v[218:219], s[38:39], 0, v[170:171]
	s_add_i32 m0, s52, 0xc000
	ds_read_b128 v[174:177], v191
	ds_read_b128 v[194:197], v191 offset:2048
	ds_read_b128 v[178:181], v192
	ds_read_b128 v[198:201], v192 offset:2048
	ds_read_b128 v[202:205], v191 offset:4096
	ds_read_b128 v[210:213], v191 offset:6144
	ds_read_b128 v[206:209], v192 offset:4096
	ds_read_b128 v[214:217], v192 offset:6144
	global_load_lds_dwordx4 v[218:219], off
	v_lshl_add_u64 v[218:219], s[38:39], 0, v[172:173]
	s_add_i32 m0, s52, 0xe000
	s_nop 0
	global_load_lds_dwordx4 v[218:219], off
	s_waitcnt vmcnt(8)
	s_waitcnt lgkmcnt(0)
	s_barrier
	s_waitcnt lgkmcnt(0)
	v_mfma_scale_f32_16x16x128_f8f6f4 v[158:161], v[18:25], v[174:181], v[158:161], v1, v182 op_sel_hi:[0,0,0]
	v_mfma_scale_f32_16x16x128_f8f6f4 v[154:157], v[26:33], v[174:181], v[154:157], v1, v182 op_sel_hi:[0,0,0]
	v_mfma_scale_f32_16x16x128_f8f6f4 v[150:153], v[18:25], v[194:201], v[150:153], v1, v182 op_sel_hi:[0,0,0]
	v_mfma_scale_f32_16x16x128_f8f6f4 v[138:141], v[26:33], v[194:201], v[138:141], v1, v182 op_sel_hi:[0,0,0]
	v_mfma_scale_f32_16x16x128_f8f6f4 v[130:133], v[18:25], v[202:209], v[130:133], v1, v182 op_sel_hi:[0,0,0]
	v_mfma_scale_f32_16x16x128_f8f6f4 v[122:125], v[26:33], v[202:209], v[122:125], v1, v182 op_sel_hi:[0,0,0]
	v_mfma_scale_f32_16x16x128_f8f6f4 v[118:121], v[18:25], v[210:217], v[118:121], v1, v182 op_sel_hi:[0,0,0]
	v_mfma_scale_f32_16x16x128_f8f6f4 v[106:109], v[26:33], v[210:217], v[106:109], v1, v182 op_sel_hi:[0,0,0]
	v_mfma_scale_f32_16x16x128_f8f6f4 v[146:149], v[2:9], v[174:181], v[146:149], v1, v182 op_sel_hi:[0,0,0]
	v_mfma_scale_f32_16x16x128_f8f6f4 v[142:145], v[10:17], v[174:181], v[142:145], v1, v182 op_sel_hi:[0,0,0]
	v_mfma_scale_f32_16x16x128_f8f6f4 v[134:137], v[2:9], v[194:201], v[134:137], v1, v182 op_sel_hi:[0,0,0]
	v_mfma_scale_f32_16x16x128_f8f6f4 v[126:129], v[10:17], v[194:201], v[126:129], v1, v182 op_sel_hi:[0,0,0]
	v_mfma_scale_f32_16x16x128_f8f6f4 v[114:117], v[2:9], v[202:209], v[114:117], v1, v182 op_sel_hi:[0,0,0]
	v_mfma_scale_f32_16x16x128_f8f6f4 v[110:113], v[10:17], v[202:209], v[110:113], v1, v182 op_sel_hi:[0,0,0]
	v_mfma_scale_f32_16x16x128_f8f6f4 v[102:105], v[2:9], v[210:217], v[102:105], v1, v182 op_sel_hi:[0,0,0]
	v_mfma_scale_f32_16x16x128_f8f6f4 v[98:101], v[10:17], v[210:217], v[98:101], v1, v182 op_sel_hi:[0,0,0]
	s_barrier
	s_add_i32 s83, s63, s45
	v_lshl_add_u64 v[174:175], s[34:35], 0, v[164:165]
	s_mov_b32 m0, s83
	ds_read_b128 v[194:197], v191 offset:16384
	ds_read_b128 v[202:205], v191 offset:18432
	ds_read_b128 v[198:201], v192 offset:16384
	ds_read_b128 v[206:209], v192 offset:18432
	ds_read_b128 v[210:213], v191 offset:20480
	ds_read_b128 v[218:221], v191 offset:22528
	ds_read_b128 v[214:217], v192 offset:20480
	ds_read_b128 v[222:225], v192 offset:22528
	global_load_lds_dwordx4 v[174:175], off
	s_add_i32 m0, s83, 0x2000
	s_add_u32 s84, s34, 0xb0000
	v_lshl_add_u64 v[176:177], s[34:35], 0, v[168:169]
	s_addc_u32 s85, s35, 0
	s_add_i32 s83, s64, s45
	global_load_lds_dwordx4 v[176:177], off
	v_lshl_add_u64 v[178:179], s[84:85], 0, v[164:165]
	s_mov_b32 m0, s83
	v_lshl_add_u64 v[180:181], s[40:41], 0, v[166:167]
	global_load_lds_dwordx4 v[178:179], off
	v_lshl_add_u64 v[178:179], s[84:85], 0, v[168:169]
	s_add_i32 m0, s83, 0x2000
	s_nop 0
	global_load_lds_dwordx4 v[178:179], off
	v_lshl_add_u64 v[178:179], s[40:41], 0, v[162:163]
	s_mov_b32 m0, s52
	s_nop 0
	global_load_lds_dwordx4 v[178:179], off
	s_mov_b32 m0, s53
	s_nop 0
	global_load_lds_dwordx4 v[180:181], off
	s_waitcnt vmcnt(8)
	s_waitcnt lgkmcnt(0)
	s_barrier
	s_waitcnt lgkmcnt(0)
	v_mfma_scale_f32_16x16x128_f8f6f4 v[94:97], v[18:25], v[194:201], v[94:97], v1, v182 op_sel_hi:[0,0,0]
	v_mfma_scale_f32_16x16x128_f8f6f4 v[90:93], v[26:33], v[194:201], v[90:93], v1, v182 op_sel_hi:[0,0,0]
	v_mfma_scale_f32_16x16x128_f8f6f4 v[82:85], v[18:25], v[202:209], v[82:85], v1, v182 op_sel_hi:[0,0,0]
	v_mfma_scale_f32_16x16x128_f8f6f4 v[74:77], v[26:33], v[202:209], v[74:77], v1, v182 op_sel_hi:[0,0,0]
	v_mfma_scale_f32_16x16x128_f8f6f4 v[66:69], v[18:25], v[210:217], v[66:69], v1, v182 op_sel_hi:[0,0,0]
	v_mfma_scale_f32_16x16x128_f8f6f4 v[58:61], v[26:33], v[210:217], v[58:61], v1, v182 op_sel_hi:[0,0,0]
	v_mfma_scale_f32_16x16x128_f8f6f4 v[50:53], v[18:25], v[218:225], v[50:53], v1, v182 op_sel_hi:[0,0,0]
	v_mfma_scale_f32_16x16x128_f8f6f4 v[42:45], v[26:33], v[218:225], v[42:45], v1, v182 op_sel_hi:[0,0,0]
	v_mfma_scale_f32_16x16x128_f8f6f4 v[86:89], v[2:9], v[194:201], v[86:89], v1, v182 op_sel_hi:[0,0,0]
	v_mfma_scale_f32_16x16x128_f8f6f4 v[78:81], v[10:17], v[194:201], v[78:81], v1, v182 op_sel_hi:[0,0,0]
	v_mfma_scale_f32_16x16x128_f8f6f4 v[70:73], v[2:9], v[202:209], v[70:73], v1, v182 op_sel_hi:[0,0,0]
	v_mfma_scale_f32_16x16x128_f8f6f4 v[62:65], v[10:17], v[202:209], v[62:65], v1, v182 op_sel_hi:[0,0,0]
	v_mfma_scale_f32_16x16x128_f8f6f4 v[54:57], v[2:9], v[210:217], v[54:57], v1, v182 op_sel_hi:[0,0,0]
	v_mfma_scale_f32_16x16x128_f8f6f4 v[46:49], v[10:17], v[210:217], v[46:49], v1, v182 op_sel_hi:[0,0,0]
	v_mfma_scale_f32_16x16x128_f8f6f4 v[38:41], v[2:9], v[218:225], v[38:41], v1, v182 op_sel_hi:[0,0,0]
	v_mfma_scale_f32_16x16x128_f8f6f4 v[34:37], v[10:17], v[218:225], v[34:37], v1, v182 op_sel_hi:[0,0,0]
	s_barrier
; #define PG8_STAGE(bufoff, gbase, voff) do { _Pragma("unroll") for (int _i = 0; _i < 2; ++_i) \
;         __builtin_amdgcn_global_load_lds((const unsigned*)((const char*)(gbase) + (voff)[_i]), (PG8_LAS unsigned*)(lds + (bufoff) + ldsw + _i * 8192), 16, 0, 0); } while (0)
; #define PG8_LDA(dst, b, h) do { _Pragma("unroll") for (int m = 0; m < 4; ++m) _Pragma("unroll") for (int k = 0; k < 2; ++k) dst[m][k] = *(const PG8_LAS bf16x8*)(lds + PG8_SA(b, h) + aoff + m * 2048 + k * 1024); } while (0)
; #define PG8_LDB(dst, b, h) do { _Pragma("unroll") for (int n = 0; n < 2; ++n) _Pragma("unroll") for (int k = 0; k < 2; ++k) dst[n][k] = *(const PG8_LAS bf16x8*)(lds + PG8_SB(b, h) + boff + n * 2048 + k * 1024); } while (0)
; #define PG8_MMA(ai, bj, At, Bt) do { __builtin_amdgcn_s_setprio(1); _Pragma("unroll") for (int m = 0; m < 4; ++m) _Pragma("unroll") for (int n = 0; n < 2; ++n) _Pragma("unroll") for (int k = 0; k < 2; ++k) \
;         acc[ai][bj][m][n] = __builtin_amdgcn_mfma_f32_16x16x32_bf16(Bt[n][k], At[m][k], acc[ai][bj][m][n], 0, 0, 0); __builtin_amdgcn_s_setprio(0); } while (0)
; #define PG8_WAIT_V(n) asm volatile("s_waitcnt vmcnt(" #n ")" ::: "memory")
; #define PG8_WAIT_L(n) asm volatile("s_waitcnt lgkmcnt(" #n ")" ::: "memory")
; #define PG8_BAR __builtin_amdgcn_s_barrier()
; #define PG8_SCHED __builtin_amdgcn_sched_barrier(0)
; #define PG8_STAGE(bufoff, gbase, voff) do { _Pragma("unroll") for (int _i = 0; _i < 2; ++_i) \
;         __builtin_amdgcn_global_load_lds((const unsigned*)((const char*)(gbase) + (voff)[_i]), (PG8_LAS unsigned*)(lds + (bufoff) + ldsw + _i * 8192), 16, 0, 0); } while (0)
; #define PG8_BAR __builtin_amdgcn_s_barrier()
; template <class Epi, class Sched, bool ALIGN_EPI = false>
; __device__ __forceinline__ void gemm_phase8(PG8_LAS unsigned char* lds, const Gemm g, const Sched& S, const Epi& E) {
;     ...
;             PG8_LDB(B0, 1, 0); PG8_LDB(B1, 1, 1); PG8_SCHED; PG8_LDA(At, 1, 0); PG8_STAGE(PG8_SA(0, 1), a2 + hstepA, voffA);
;             PG8_WAIT_V(8); PG8_WAIT_L(0); PG8_BAR; PG8_MMA(0, 0, At, B0); PG8_MMA(0, 1, At, B1); PG8_BAR; PG8_SCHED;
;             PG8_LDA(At, 1, 1); PG8_STAGE(PG8_SB(1, 0), b3, voffB); PG8_STAGE(PG8_SB(1, 1), b3 + hstepB, voffB); PG8_STAGE(PG8_SA(1, 0), a3, voffA);
;             PG8_WAIT_V(8); PG8_WAIT_L(0); PG8_BAR; PG8_MMA(1, 0, At, B0); PG8_MMA(1, 1, At, B1); PG8_BAR; PG8_SCHED;
;         }
	s_add_i32 s83, 0, 0x18000
	s_add_i32 s84, 0, 0x1c000
	v_add_u32_e32 v6, s83, v184
	v_add_u32_e32 v14, s83, v185
	v_add_u32_e32 v22, s84, v184
	v_add_u32_e32 v30, s84, v185
	ds_read_b128 v[2:5], v6
	ds_read_b128 v[10:13], v6 offset:2048
	ds_read_b128 v[6:9], v14
	ds_read_b128 v[14:17], v14 offset:2048
	ds_read_b128 v[18:21], v22
	ds_read_b128 v[26:29], v22 offset:2048
	ds_read_b128 v[22:25], v30
	ds_read_b128 v[30:33], v30 offset:2048
	s_add_u32 s40, s40, 0xb0000
	s_addc_u32 s41, s41, 0
	s_mov_b32 m0, s54
	v_lshl_add_u64 v[226:227], s[40:41], 0, v[162:163]
	ds_read_b128 v[194:197], v191 offset:32768
	ds_read_b128 v[202:205], v191 offset:34816
	ds_read_b128 v[198:201], v192 offset:32768
	ds_read_b128 v[206:209], v192 offset:34816
	ds_read_b128 v[210:213], v191 offset:36864
	ds_read_b128 v[218:221], v191 offset:38912
	ds_read_b128 v[214:217], v192 offset:36864
	ds_read_b128 v[222:225], v192 offset:38912
	global_load_lds_dwordx4 v[226:227], off
	v_lshl_add_u64 v[226:227], s[40:41], 0, v[166:167]
	s_mov_b32 m0, s55
	s_nop 0
	global_load_lds_dwordx4 v[226:227], off
	s_waitcnt vmcnt(8)
	s_waitcnt lgkmcnt(0)
	s_barrier
	s_waitcnt lgkmcnt(0)
	v_mfma_scale_f32_16x16x128_f8f6f4 v[158:161], v[2:9], v[194:201], v[158:161], v1, v182 op_sel_hi:[0,0,0]
	v_mfma_scale_f32_16x16x128_f8f6f4 v[154:157], v[10:17], v[194:201], v[154:157], v1, v182 op_sel_hi:[0,0,0]
	v_mfma_scale_f32_16x16x128_f8f6f4 v[150:153], v[2:9], v[202:209], v[150:153], v1, v182 op_sel_hi:[0,0,0]
	v_mfma_scale_f32_16x16x128_f8f6f4 v[138:141], v[10:17], v[202:209], v[138:141], v1, v182 op_sel_hi:[0,0,0]
	v_mfma_scale_f32_16x16x128_f8f6f4 v[130:133], v[2:9], v[210:217], v[130:133], v1, v182 op_sel_hi:[0,0,0]
	v_mfma_scale_f32_16x16x128_f8f6f4 v[122:125], v[10:17], v[210:217], v[122:125], v1, v182 op_sel_hi:[0,0,0]
	v_mfma_scale_f32_16x16x128_f8f6f4 v[118:121], v[2:9], v[218:225], v[118:121], v1, v182 op_sel_hi:[0,0,0]
	v_mfma_scale_f32_16x16x128_f8f6f4 v[106:109], v[10:17], v[218:225], v[106:109], v1, v182 op_sel_hi:[0,0,0]
	v_mfma_scale_f32_16x16x128_f8f6f4 v[146:149], v[18:25], v[194:201], v[146:149], v1, v182 op_sel_hi:[0,0,0]
	v_mfma_scale_f32_16x16x128_f8f6f4 v[142:145], v[26:33], v[194:201], v[142:145], v1, v182 op_sel_hi:[0,0,0]
	v_mfma_scale_f32_16x16x128_f8f6f4 v[134:137], v[18:25], v[202:209], v[134:137], v1, v182 op_sel_hi:[0,0,0]
	v_mfma_scale_f32_16x16x128_f8f6f4 v[126:129], v[26:33], v[202:209], v[126:129], v1, v182 op_sel_hi:[0,0,0]
	v_mfma_scale_f32_16x16x128_f8f6f4 v[114:117], v[18:25], v[210:217], v[114:117], v1, v182 op_sel_hi:[0,0,0]
	v_mfma_scale_f32_16x16x128_f8f6f4 v[110:113], v[26:33], v[210:217], v[110:113], v1, v182 op_sel_hi:[0,0,0]
	v_mfma_scale_f32_16x16x128_f8f6f4 v[102:105], v[18:25], v[218:225], v[102:105], v1, v182 op_sel_hi:[0,0,0]
	v_mfma_scale_f32_16x16x128_f8f6f4 v[98:101], v[26:33], v[218:225], v[98:101], v1, v182 op_sel_hi:[0,0,0]
	s_barrier
	s_add_i32 s40, s83, s45
	v_lshl_add_u64 v[174:175], v[174:175], 0, s[12:13]
	s_mov_b32 m0, s40
	ds_read_b128 v[194:197], v191 offset:49152
	ds_read_b128 v[202:205], v191 offset:51200
	ds_read_b128 v[198:201], v192 offset:49152
	ds_read_b128 v[206:209], v192 offset:51200
	ds_read_b128 v[210:213], v191 offset:53248
	ds_read_b128 v[218:221], v191 offset:55296
	ds_read_b128 v[214:217], v192 offset:53248
	ds_read_b128 v[222:225], v192 offset:55296
	global_load_lds_dwordx4 v[174:175], off
	s_add_i32 m0, s40, 0x2000
	s_add_u32 s34, s34, 0xb0080
	v_lshl_add_u64 v[174:175], v[176:177], 0, s[12:13]
	s_addc_u32 s35, s35, 0
	s_add_i32 s40, s84, s45
	global_load_lds_dwordx4 v[174:175], off
	v_lshl_add_u64 v[174:175], s[34:35], 0, v[164:165]
	s_mov_b32 m0, s40
	s_nop 0
	global_load_lds_dwordx4 v[174:175], off
	v_lshl_add_u64 v[174:175], s[34:35], 0, v[168:169]
	s_add_i32 m0, s40, 0x2000
	s_nop 0
	global_load_lds_dwordx4 v[174:175], off
	v_lshl_add_u64 v[174:175], v[178:179], 0, s[12:13]
	s_mov_b32 m0, s61
	s_nop 0
	global_load_lds_dwordx4 v[174:175], off
	v_lshl_add_u64 v[174:175], v[180:181], 0, s[12:13]
	s_mov_b32 m0, s62
	s_nop 0
	global_load_lds_dwordx4 v[174:175], off
	s_waitcnt vmcnt(8)
	s_waitcnt lgkmcnt(0)
	s_barrier
	s_waitcnt lgkmcnt(0)
	v_mfma_scale_f32_16x16x128_f8f6f4 v[94:97], v[2:9], v[194:201], v[94:97], v1, v182 op_sel_hi:[0,0,0]
	v_mfma_scale_f32_16x16x128_f8f6f4 v[90:93], v[10:17], v[194:201], v[90:93], v1, v182 op_sel_hi:[0,0,0]
	v_mfma_scale_f32_16x16x128_f8f6f4 v[82:85], v[2:9], v[202:209], v[82:85], v1, v182 op_sel_hi:[0,0,0]
	v_mfma_scale_f32_16x16x128_f8f6f4 v[74:77], v[10:17], v[202:209], v[74:77], v1, v182 op_sel_hi:[0,0,0]
	v_mfma_scale_f32_16x16x128_f8f6f4 v[66:69], v[2:9], v[210:217], v[66:69], v1, v182 op_sel_hi:[0,0,0]
	v_mfma_scale_f32_16x16x128_f8f6f4 v[58:61], v[10:17], v[210:217], v[58:61], v1, v182 op_sel_hi:[0,0,0]
	v_mfma_scale_f32_16x16x128_f8f6f4 v[50:53], v[2:9], v[218:225], v[50:53], v1, v182 op_sel_hi:[0,0,0]
	v_mfma_scale_f32_16x16x128_f8f6f4 v[42:45], v[10:17], v[218:225], v[42:45], v1, v182 op_sel_hi:[0,0,0]
	v_mfma_scale_f32_16x16x128_f8f6f4 v[86:89], v[18:25], v[194:201], v[86:89], v1, v182 op_sel_hi:[0,0,0]
	v_mfma_scale_f32_16x16x128_f8f6f4 v[78:81], v[26:33], v[194:201], v[78:81], v1, v182 op_sel_hi:[0,0,0]
	v_mfma_scale_f32_16x16x128_f8f6f4 v[70:73], v[18:25], v[202:209], v[70:73], v1, v182 op_sel_hi:[0,0,0]
	v_mfma_scale_f32_16x16x128_f8f6f4 v[62:65], v[26:33], v[202:209], v[62:65], v1, v182 op_sel_hi:[0,0,0]
	v_mfma_scale_f32_16x16x128_f8f6f4 v[54:57], v[18:25], v[210:217], v[54:57], v1, v182 op_sel_hi:[0,0,0]
	v_mfma_scale_f32_16x16x128_f8f6f4 v[46:49], v[26:33], v[210:217], v[46:49], v1, v182 op_sel_hi:[0,0,0]
	v_mfma_scale_f32_16x16x128_f8f6f4 v[38:41], v[18:25], v[218:225], v[38:41], v1, v182 op_sel_hi:[0,0,0]
	v_mfma_scale_f32_16x16x128_f8f6f4 v[34:37], v[26:33], v[218:225], v[34:37], v1, v182 op_sel_hi:[0,0,0]
	s_barrier
	s_add_u32 s38, s38, 0x100
	s_addc_u32 s39, s39, 0
	s_add_u32 s80, s80, 0x100
	s_addc_u32 s81, s81, 0
	s_cmp_ge_u32 s82, s31
	s_mov_b32 s40, s82
	s_cbranch_scc0 .LBB0_1511
	s_and_b64 vcc, exec, s[14:15]
	s_cbranch_vccz .LBB0_1514
	s_barrier
